# S5 pass2: state rows stored re/im-interleaved with one 32-bit LDS write per step (C fragments permuted to match)
# speedup vs baseline: 1.0124x; 1.0067x over previous
.LBB0_1779:
	s_or_b64 exec, exec, s[0:1]
	v_bfe_u32 v83, v4, 4, 2
	v_lshlrev_b32_e32 v2, 3, v83
	v_lshl_add_u64 v[0:1], s[46:47], 0, v[0:1]
	v_lshlrev_b32_e32 v128, 8, v79
	v_lshl_add_u64 v[0:1], v[0:1], 0, v[128:129]
	v_mov_b32_e32 v156, v2
	v_mov_b32_e32 v157, 0
	v_lshl_add_u64 v[156:157], v[0:1], 0, v[156:157]
	v_lshlrev_b32_e32 v128, 1, v2
	v_lshl_add_u64 v[0:1], v[0:1], 0, v[128:129]
	global_load_dwordx2 v[140:141], v[156:157], off
	global_load_dwordx2 v[142:143], v[156:157], off offset:128
	global_load_dwordx2 v[144:145], v[156:157], off offset:32
	global_load_dwordx2 v[146:147], v[156:157], off offset:160
	global_load_dwordx2 v[148:149], v[156:157], off offset:64
	global_load_dwordx2 v[150:151], v[156:157], off offset:192
	global_load_dwordx2 v[152:153], v[156:157], off offset:96
	global_load_dwordx2 v[154:155], v[156:157], off offset:224
	v_lshlrev_b32_e32 v80, 4, v76
	v_ashrrev_i32_e32 v81, 31, v80
	v_add_u32_e32 v72, s8, v79
	v_lshl_add_u64 v[68:69], v[80:81], 1, s[36:37]
	v_lshl_add_u64 v[74:75], v[68:69], 0, v[128:129]
	v_mov_b32_e32 v4, 0
	v_ashrrev_i32_e32 v73, 31, v72
	v_mov_b32_e32 v0, 0
	v_mov_b32_e32 v1, 0
	v_mov_b32_e32 v2, 0
	v_mov_b32_e32 v3, 0
	s_and_saveexec_b64 s[0:1], s[42:43]
	s_cbranch_execz .LBB0_1781
	v_lshlrev_b64 v[0:1], 10, v[72:73]
	v_lshl_add_u64 v[0:1], v[74:75], 0, v[0:1]
	global_load_dwordx4 v[0:3], v[0:1], off

.LBB0_1787:
	s_or_b64 exec, exec, s[0:1]
	s_movk_i32 s1, 0x3200
	v_mul_lo_u32 v72, v82, s1
	v_add_u32_e32 v81, 0, v72
	s_waitcnt vmcnt(0) lgkmcnt(0)
	v_mov_b32_e32 v158, 0x5040100
	v_mov_b32_e32 v159, 0x7060302
	v_perm_b32 v24, v142, v140, v158
	v_perm_b32 v25, v142, v140, v159
	v_perm_b32 v26, v143, v141, v158
	v_perm_b32 v27, v143, v141, v159
	v_perm_b32 v20, v146, v144, v158
	v_perm_b32 v21, v146, v144, v159
	v_perm_b32 v22, v147, v145, v158
	v_perm_b32 v23, v147, v145, v159
	v_perm_b32 v16, v150, v148, v158
	v_perm_b32 v17, v150, v148, v159
	v_perm_b32 v18, v151, v149, v158
	v_perm_b32 v19, v151, v149, v159
	v_perm_b32 v12, v154, v152, v158
	v_perm_b32 v13, v154, v152, v159
	v_perm_b32 v14, v155, v153, v158
	v_perm_b32 v15, v155, v153, v159
	v_mfma_f32_16x16x32_bf16 v[84:87], v[0:3], v[32:35], 0
	v_mul_u32_u24_e32 v72, 0x210, v83
	v_lshlrev_b32_e32 v73, 2, v79
	v_lshlrev_b32_e32 v72, 2, v72
	v_mfma_f32_16x16x32_bf16 v[96:99], v[0:3], v[28:31], 0
	v_add3_u32 v73, v81, v73, v72
	v_add_u32_e32 v74, 0x400, v73
	s_nop 5
	ds_write2_b32 v73, v84, v96 offset1:16
	ds_write2_b32 v73, v85, v97 offset0:132 offset1:148
	ds_write2_b32 v74, v86, v98 offset0:8 offset1:24
	ds_write2_b32 v74, v87, v99 offset0:140 offset1:156
	v_mfma_f32_16x16x32_bf16 v[82:85], v[0:3], v[40:43], 0
	v_lshl_add_u32 v75, v78, 2, v81
	s_cmp_gt_i32 s9, 3
	s_cselect_b32 s0, 0x87, 3
	v_mfma_f32_16x16x32_bf16 v[86:89], v[0:3], v[36:39], 0
	s_nop 7
	ds_write2_b32 v73, v82, v86 offset0:32 offset1:48
	ds_write2_b32 v73, v83, v87 offset0:164 offset1:180
	ds_write2_b32 v74, v84, v88 offset0:40 offset1:56
	ds_write2_b32 v74, v85, v89 offset0:172 offset1:188
	v_mfma_f32_16x16x32_bf16 v[82:85], v[0:3], v[48:51], 0
	s_sub_i32 s0, s0, s9
	v_mul_u32_u24_e32 v94, 0x110, v79
	v_add_u32_e32 v79, 64, v75
	v_mfma_f32_16x16x32_bf16 v[86:89], v[0:3], v[44:47], 0
	s_nop 7
	ds_write2_b32 v73, v82, v86 offset0:64 offset1:80
	ds_write2_b32 v73, v83, v87 offset0:196 offset1:212
	ds_write2_b32 v74, v84, v88 offset0:72 offset1:88
	ds_write2_b32 v74, v85, v89 offset0:204 offset1:220
	v_mfma_f32_16x16x32_bf16 v[82:85], v[0:3], v[56:59], 0
	v_add_u32_e32 v86, 0x90, v75
	v_add_u32_e32 v87, 0xa0, v75
	v_add_u32_e32 v88, 0xb0, v75
	v_mfma_f32_16x16x32_bf16 v[0:3], v[0:3], v[52:55], 0
	s_nop 7
	ds_write2_b32 v73, v82, v0 offset0:96 offset1:112
	ds_write2_b32 v73, v83, v1 offset0:228 offset1:244
	ds_write2_b32 v74, v84, v2 offset0:104 offset1:120
	ds_write2_b32 v74, v85, v3 offset0:236 offset1:252
	v_lshlrev_b32_e32 v0, 1, v78
	s_waitcnt vmcnt(0) lgkmcnt(0)
	v_sub_u32_e32 v72, v75, v0
	ds_read2st64_b32 v[0:1], v75 offset1:1
	ds_read2_b32 v[140:141], v75 offset0:132 offset1:196
	v_add_u32_e32 v142, 32, v75
	ds_read2st64_b32 v[144:145], v142 offset0:4 offset1:5
	v_add_u32_e32 v143, 48, v75
	ds_read2st64_b32 v[146:147], v143 offset0:6 offset1:7
	ds_read2st64_b32 v[148:149], v79 offset0:8 offset1:9
	v_add_u32_e32 v150, 0x50, v75
	ds_read2st64_b32 v[152:153], v150 offset0:10 offset1:11
	v_add_u32_e32 v151, 0x60, v75
	ds_read2st64_b32 v[154:155], v151 offset0:12 offset1:13
	v_add_u32_e32 v156, 0x70, v75
	ds_read2st64_b32 v[158:159], v156 offset0:14 offset1:15
	v_add_u32_e32 v157, 0x80, v75
	ds_read2st64_b32 v[160:161], v157 offset0:16 offset1:17
	ds_read2st64_b32 v[162:163], v86 offset0:18 offset1:19
	ds_read2st64_b32 v[164:165], v87 offset0:20 offset1:21
	ds_read2st64_b32 v[166:167], v88 offset0:22 offset1:23
	v_add_u32_e32 v168, 0xc0, v75
	ds_read2st64_b32 v[170:171], v168 offset0:24 offset1:25
	v_add_u32_e32 v169, 0xd0, v75
	ds_read2st64_b32 v[172:173], v169 offset0:26 offset1:27
	v_add_u32_e32 v174, 0xe0, v75
	ds_read2st64_b32 v[176:177], v174 offset0:28 offset1:29
	v_add_u32_e32 v175, 0xf0, v75
	ds_read2st64_b32 v[178:179], v175 offset0:30 offset1:31
	v_mov_b32_e32 v186, v70
	v_mov_b32_e32 v187, v71
	v_add_u32_e32 v78, 48, v75
	v_add_u32_e32 v82, 0x50, v75
	s_waitcnt lgkmcnt(0)
	v_pk_fma_f32 v[184:185], v[66:67], v[186:187], v[0:1] op_sel:[1,1,0] op_sel_hi:[1,0,1] neg_lo:[1,0,0]
	v_pk_fma_f32 v[188:189], v[66:67], v[186:187], v[184:185] op_sel_hi:[0,1,1]
	v_cvt_pk_bf16_f32 v190, v188, v189
	v_and_b32_e32 v191, 63, v207
	v_lshl_add_u32 v191, v191, 1, v72
	ds_write_b32 v191, v190 offset:8448
	v_add_u32_e32 v71, 32, v75
	v_add_u32_e32 v83, 0x60, v75
	v_pk_fma_f32 v[184:185], v[66:67], v[188:189], v[140:141] op_sel:[1,1,0] op_sel_hi:[1,0,1] neg_lo:[1,0,0]
	v_pk_fma_f32 v[186:187], v[66:67], v[188:189], v[184:185] op_sel_hi:[0,1,1]
	v_cvt_pk_bf16_f32 v190, v186, v187
	ds_write_b32 v191, v190 offset:8720
	v_add_u32_e32 v84, 0x70, v75
	v_add_u32_e32 v85, 0x80, v75
	v_pk_fma_f32 v[184:185], v[66:67], v[186:187], v[144:145] op_sel:[1,1,0] op_sel_hi:[1,0,1] neg_lo:[1,0,0]
	v_pk_fma_f32 v[188:189], v[66:67], v[186:187], v[184:185] op_sel_hi:[0,1,1]
	v_cvt_pk_bf16_f32 v190, v188, v189
	ds_write_b32 v191, v190 offset:8992
	v_add_u32_e32 v89, 0xc0, v75
	v_add_u32_e32 v91, 0xd0, v75
	v_pk_fma_f32 v[184:185], v[66:67], v[188:189], v[146:147] op_sel:[1,1,0] op_sel_hi:[1,0,1] neg_lo:[1,0,0]
	v_pk_fma_f32 v[186:187], v[66:67], v[188:189], v[184:185] op_sel_hi:[0,1,1]
	v_cvt_pk_bf16_f32 v190, v186, v187
	ds_write_b32 v191, v190 offset:9264
	v_add_u32_e32 v92, 0xe0, v75
	v_add_u32_e32 v93, 0xf0, v75
	v_pk_fma_f32 v[184:185], v[66:67], v[186:187], v[148:149] op_sel:[1,1,0] op_sel_hi:[1,0,1] neg_lo:[1,0,0]
	v_pk_fma_f32 v[188:189], v[66:67], v[186:187], v[184:185] op_sel_hi:[0,1,1]
	v_cvt_pk_bf16_f32 v190, v188, v189
	ds_write_b32 v191, v190 offset:9536
	v_mfma_f32_16x16x32_bf16 v[98:101], v[4:7], v[28:31], 0
	s_or_b32 s1, s2, 0x84
	v_pk_fma_f32 v[184:185], v[66:67], v[188:189], v[152:153] op_sel:[1,1,0] op_sel_hi:[1,0,1] neg_lo:[1,0,0]
	v_pk_fma_f32 v[186:187], v[66:67], v[188:189], v[184:185] op_sel_hi:[0,1,1]
	v_cvt_pk_bf16_f32 v190, v186, v187
	ds_write_b32 v191, v190 offset:9808
	s_ashr_i32 s2, s0, 31
	v_pk_fma_f32 v[184:185], v[66:67], v[186:187], v[154:155] op_sel:[1,1,0] op_sel_hi:[1,0,1] neg_lo:[1,0,0]
	v_pk_fma_f32 v[188:189], v[66:67], v[186:187], v[184:185] op_sel_hi:[0,1,1]
	v_cvt_pk_bf16_f32 v190, v188, v189
	ds_write_b32 v191, v190 offset:10080
	v_pk_fma_f32 v[184:185], v[66:67], v[188:189], v[158:159] op_sel:[1,1,0] op_sel_hi:[1,0,1] neg_lo:[1,0,0]
	v_pk_fma_f32 v[186:187], v[66:67], v[188:189], v[184:185] op_sel_hi:[0,1,1]
	v_cvt_pk_bf16_f32 v190, v186, v187
	ds_write_b32 v191, v190 offset:10352
	v_pk_fma_f32 v[184:185], v[66:67], v[186:187], v[160:161] op_sel:[1,1,0] op_sel_hi:[1,0,1] neg_lo:[1,0,0]
	v_pk_fma_f32 v[188:189], v[66:67], v[186:187], v[184:185] op_sel_hi:[0,1,1]
	v_cvt_pk_bf16_f32 v190, v188, v189
	ds_write_b32 v191, v190 offset:10624
	v_pk_fma_f32 v[184:185], v[66:67], v[188:189], v[162:163] op_sel:[1,1,0] op_sel_hi:[1,0,1] neg_lo:[1,0,0]
	v_pk_fma_f32 v[186:187], v[66:67], v[188:189], v[184:185] op_sel_hi:[0,1,1]
	v_cvt_pk_bf16_f32 v190, v186, v187
	ds_write_b32 v191, v190 offset:10896
	v_pk_fma_f32 v[184:185], v[66:67], v[186:187], v[164:165] op_sel:[1,1,0] op_sel_hi:[1,0,1] neg_lo:[1,0,0]
	v_pk_fma_f32 v[188:189], v[66:67], v[186:187], v[184:185] op_sel_hi:[0,1,1]
	v_cvt_pk_bf16_f32 v190, v188, v189
	ds_write_b32 v191, v190 offset:11168
	v_pk_fma_f32 v[184:185], v[66:67], v[188:189], v[166:167] op_sel:[1,1,0] op_sel_hi:[1,0,1] neg_lo:[1,0,0]
	v_pk_fma_f32 v[186:187], v[66:67], v[188:189], v[184:185] op_sel_hi:[0,1,1]
	v_cvt_pk_bf16_f32 v190, v186, v187
	ds_write_b32 v191, v190 offset:11440
	v_pk_fma_f32 v[184:185], v[66:67], v[186:187], v[170:171] op_sel:[1,1,0] op_sel_hi:[1,0,1] neg_lo:[1,0,0]
	v_pk_fma_f32 v[188:189], v[66:67], v[186:187], v[184:185] op_sel_hi:[0,1,1]
	v_cvt_pk_bf16_f32 v190, v188, v189
	ds_write_b32 v191, v190 offset:11712
	v_pk_fma_f32 v[184:185], v[66:67], v[188:189], v[172:173] op_sel:[1,1,0] op_sel_hi:[1,0,1] neg_lo:[1,0,0]
	v_pk_fma_f32 v[186:187], v[66:67], v[188:189], v[184:185] op_sel_hi:[0,1,1]
	v_cvt_pk_bf16_f32 v190, v186, v187
	ds_write_b32 v191, v190 offset:11984
	v_pk_fma_f32 v[184:185], v[66:67], v[186:187], v[176:177] op_sel:[1,1,0] op_sel_hi:[1,0,1] neg_lo:[1,0,0]
	v_pk_fma_f32 v[188:189], v[66:67], v[186:187], v[184:185] op_sel_hi:[0,1,1]
	v_cvt_pk_bf16_f32 v190, v188, v189
	ds_write_b32 v191, v190 offset:12256
	v_pk_fma_f32 v[184:185], v[66:67], v[188:189], v[178:179] op_sel:[1,1,0] op_sel_hi:[1,0,1] neg_lo:[1,0,0]
	v_pk_fma_f32 v[186:187], v[66:67], v[188:189], v[184:185] op_sel_hi:[0,1,1]
	v_mov_b32_e32 v102, v186
	v_mov_b32_e32 v103, v187
	v_cvt_pk_bf16_f32 v190, v186, v187
	ds_write_b32 v191, v190 offset:12528
	v_add3_u32 v70, v81, v128, v94
	s_waitcnt vmcnt(0) lgkmcnt(0)
	ds_read_b128 v[0:3], v70 offset:8448
	ds_read_b128 v[94:97], v70 offset:8512
	s_waitcnt lgkmcnt(1)
	v_mfma_f32_16x16x32_bf16 v[0:3], v[0:3], v[24:27], 0
	s_waitcnt lgkmcnt(0)
	v_mfma_f32_16x16x32_bf16 v[0:3], v[94:97], v[20:23], v[0:3]
	ds_read_b128 v[94:97], v70 offset:8576
	s_waitcnt lgkmcnt(0)
	v_mfma_f32_16x16x32_bf16 v[0:3], v[94:97], v[16:19], v[0:3]
	ds_read_b128 v[94:97], v70 offset:8640
	s_waitcnt lgkmcnt(0)
	v_mfma_f32_16x16x32_bf16 v[0:3], v[94:97], v[12:15], v[0:3]
	v_mfma_f32_16x16x32_bf16 v[94:97], v[4:7], v[32:35], 0
	s_nop 7
	ds_write2_b32 v73, v94, v98 offset1:16
	ds_write2_b32 v73, v95, v99 offset0:132 offset1:148
	ds_write2_b32 v74, v96, v100 offset0:8 offset1:24
	ds_write2_b32 v74, v97, v101 offset0:140 offset1:156
	v_mfma_f32_16x16x32_bf16 v[94:97], v[4:7], v[40:43], 0
	v_mfma_f32_16x16x32_bf16 v[98:101], v[4:7], v[36:39], 0
	s_nop 7
	ds_write2_b32 v73, v94, v98 offset0:32 offset1:48
	ds_write2_b32 v73, v95, v99 offset0:164 offset1:180
	ds_write2_b32 v74, v96, v100 offset0:40 offset1:56
	ds_write2_b32 v74, v97, v101 offset0:172 offset1:188
	v_mfma_f32_16x16x32_bf16 v[94:97], v[4:7], v[48:51], 0
	v_mfma_f32_16x16x32_bf16 v[98:101], v[4:7], v[44:47], 0
	s_nop 7
	ds_write2_b32 v73, v94, v98 offset0:64 offset1:80
	ds_write2_b32 v73, v95, v99 offset0:196 offset1:212
	ds_write2_b32 v74, v96, v100 offset0:72 offset1:88
	ds_write2_b32 v74, v97, v101 offset0:204 offset1:220
	v_mfma_f32_16x16x32_bf16 v[94:97], v[4:7], v[56:59], 0
	v_mfma_f32_16x16x32_bf16 v[4:7], v[4:7], v[52:55], 0
	s_nop 7
	ds_write2_b32 v73, v94, v4 offset0:96 offset1:112
	ds_write2_b32 v73, v95, v5 offset0:228 offset1:244
	ds_write2_b32 v74, v96, v6 offset0:104 offset1:120
	ds_write2_b32 v74, v97, v7 offset0:236 offset1:252
	s_waitcnt vmcnt(0) lgkmcnt(0)
	ds_read2st64_b32 v[4:5], v75 offset1:1
	ds_read2_b32 v[140:141], v75 offset0:132 offset1:196
	ds_read2st64_b32 v[142:143], v71 offset0:4 offset1:5
	ds_read2st64_b32 v[144:145], v78 offset0:6 offset1:7
	ds_read2st64_b32 v[146:147], v79 offset0:8 offset1:9
	ds_read2st64_b32 v[148:149], v82 offset0:10 offset1:11
	ds_read2st64_b32 v[150:151], v83 offset0:12 offset1:13
	ds_read2st64_b32 v[152:153], v84 offset0:14 offset1:15
	ds_read2st64_b32 v[154:155], v85 offset0:16 offset1:17
	ds_read2st64_b32 v[156:157], v86 offset0:18 offset1:19
	ds_read2st64_b32 v[158:159], v87 offset0:20 offset1:21
	ds_read2st64_b32 v[160:161], v88 offset0:22 offset1:23
	ds_read2st64_b32 v[162:163], v89 offset0:24 offset1:25
	ds_read2st64_b32 v[164:165], v91 offset0:26 offset1:27
	ds_read2st64_b32 v[166:167], v92 offset0:28 offset1:29
	ds_read2st64_b32 v[168:169], v93 offset0:30 offset1:31
	v_mov_b32_e32 v186, v102
	v_mov_b32_e32 v187, v103
	v_mfma_f32_16x16x32_bf16 v[98:101], v[8:11], v[28:31], 0
	s_waitcnt lgkmcnt(0)
	v_pk_fma_f32 v[184:185], v[66:67], v[186:187], v[4:5] op_sel:[1,1,0] op_sel_hi:[1,0,1] neg_lo:[1,0,0]
	v_pk_fma_f32 v[188:189], v[66:67], v[186:187], v[184:185] op_sel_hi:[0,1,1]
	v_cvt_pk_bf16_f32 v190, v188, v189
	v_and_b32_e32 v191, 63, v207
	v_lshl_add_u32 v191, v191, 1, v72
	ds_write_b32 v191, v190 offset:8448
	v_mfma_f32_16x16x32_bf16 v[28:31], v[60:63], v[28:31], 0
	v_pk_fma_f32 v[184:185], v[66:67], v[188:189], v[140:141] op_sel:[1,1,0] op_sel_hi:[1,0,1] neg_lo:[1,0,0]
	v_pk_fma_f32 v[186:187], v[66:67], v[188:189], v[184:185] op_sel_hi:[0,1,1]
	v_cvt_pk_bf16_f32 v190, v186, v187
	ds_write_b32 v191, v190 offset:8720
	v_pk_fma_f32 v[184:185], v[66:67], v[186:187], v[142:143] op_sel:[1,1,0] op_sel_hi:[1,0,1] neg_lo:[1,0,0]
	v_pk_fma_f32 v[188:189], v[66:67], v[186:187], v[184:185] op_sel_hi:[0,1,1]
	v_cvt_pk_bf16_f32 v190, v188, v189
	ds_write_b32 v191, v190 offset:8992
	v_pk_fma_f32 v[184:185], v[66:67], v[188:189], v[144:145] op_sel:[1,1,0] op_sel_hi:[1,0,1] neg_lo:[1,0,0]
	v_pk_fma_f32 v[186:187], v[66:67], v[188:189], v[184:185] op_sel_hi:[0,1,1]
	v_cvt_pk_bf16_f32 v190, v186, v187
	ds_write_b32 v191, v190 offset:9264
	v_pk_fma_f32 v[184:185], v[66:67], v[186:187], v[146:147] op_sel:[1,1,0] op_sel_hi:[1,0,1] neg_lo:[1,0,0]
	v_pk_fma_f32 v[188:189], v[66:67], v[186:187], v[184:185] op_sel_hi:[0,1,1]
	v_cvt_pk_bf16_f32 v190, v188, v189
	ds_write_b32 v191, v190 offset:9536
	v_pk_fma_f32 v[184:185], v[66:67], v[188:189], v[148:149] op_sel:[1,1,0] op_sel_hi:[1,0,1] neg_lo:[1,0,0]
	v_pk_fma_f32 v[186:187], v[66:67], v[188:189], v[184:185] op_sel_hi:[0,1,1]
	v_cvt_pk_bf16_f32 v190, v186, v187
	ds_write_b32 v191, v190 offset:9808
	v_pk_fma_f32 v[184:185], v[66:67], v[186:187], v[150:151] op_sel:[1,1,0] op_sel_hi:[1,0,1] neg_lo:[1,0,0]
	v_pk_fma_f32 v[188:189], v[66:67], v[186:187], v[184:185] op_sel_hi:[0,1,1]
	v_cvt_pk_bf16_f32 v190, v188, v189
	ds_write_b32 v191, v190 offset:10080
	v_pk_fma_f32 v[184:185], v[66:67], v[188:189], v[152:153] op_sel:[1,1,0] op_sel_hi:[1,0,1] neg_lo:[1,0,0]
	v_pk_fma_f32 v[186:187], v[66:67], v[188:189], v[184:185] op_sel_hi:[0,1,1]
	v_cvt_pk_bf16_f32 v190, v186, v187
	ds_write_b32 v191, v190 offset:10352
	v_pk_fma_f32 v[184:185], v[66:67], v[186:187], v[154:155] op_sel:[1,1,0] op_sel_hi:[1,0,1] neg_lo:[1,0,0]
	v_pk_fma_f32 v[188:189], v[66:67], v[186:187], v[184:185] op_sel_hi:[0,1,1]
	v_cvt_pk_bf16_f32 v190, v188, v189
	ds_write_b32 v191, v190 offset:10624
	v_pk_fma_f32 v[184:185], v[66:67], v[188:189], v[156:157] op_sel:[1,1,0] op_sel_hi:[1,0,1] neg_lo:[1,0,0]
	v_pk_fma_f32 v[186:187], v[66:67], v[188:189], v[184:185] op_sel_hi:[0,1,1]
	v_cvt_pk_bf16_f32 v190, v186, v187
	ds_write_b32 v191, v190 offset:10896
	v_pk_fma_f32 v[184:185], v[66:67], v[186:187], v[158:159] op_sel:[1,1,0] op_sel_hi:[1,0,1] neg_lo:[1,0,0]
	v_pk_fma_f32 v[188:189], v[66:67], v[186:187], v[184:185] op_sel_hi:[0,1,1]
	v_cvt_pk_bf16_f32 v190, v188, v189
	ds_write_b32 v191, v190 offset:11168
	v_pk_fma_f32 v[184:185], v[66:67], v[188:189], v[160:161] op_sel:[1,1,0] op_sel_hi:[1,0,1] neg_lo:[1,0,0]
	v_pk_fma_f32 v[186:187], v[66:67], v[188:189], v[184:185] op_sel_hi:[0,1,1]
	v_cvt_pk_bf16_f32 v190, v186, v187
	ds_write_b32 v191, v190 offset:11440
	v_pk_fma_f32 v[184:185], v[66:67], v[186:187], v[162:163] op_sel:[1,1,0] op_sel_hi:[1,0,1] neg_lo:[1,0,0]
	v_pk_fma_f32 v[188:189], v[66:67], v[186:187], v[184:185] op_sel_hi:[0,1,1]
	v_cvt_pk_bf16_f32 v190, v188, v189
	ds_write_b32 v191, v190 offset:11712
	v_pk_fma_f32 v[184:185], v[66:67], v[188:189], v[164:165] op_sel:[1,1,0] op_sel_hi:[1,0,1] neg_lo:[1,0,0]
	v_pk_fma_f32 v[186:187], v[66:67], v[188:189], v[184:185] op_sel_hi:[0,1,1]
	v_cvt_pk_bf16_f32 v190, v186, v187
	ds_write_b32 v191, v190 offset:11984
	v_pk_fma_f32 v[184:185], v[66:67], v[186:187], v[166:167] op_sel:[1,1,0] op_sel_hi:[1,0,1] neg_lo:[1,0,0]
	v_pk_fma_f32 v[188:189], v[66:67], v[186:187], v[184:185] op_sel_hi:[0,1,1]
	v_cvt_pk_bf16_f32 v190, v188, v189
	ds_write_b32 v191, v190 offset:12256
	v_pk_fma_f32 v[184:185], v[66:67], v[188:189], v[168:169] op_sel:[1,1,0] op_sel_hi:[1,0,1] neg_lo:[1,0,0]
	v_pk_fma_f32 v[186:187], v[66:67], v[188:189], v[184:185] op_sel_hi:[0,1,1]
	v_mov_b32_e32 v102, v186
	v_mov_b32_e32 v103, v187
	v_cvt_pk_bf16_f32 v190, v186, v187
	ds_write_b32 v191, v190 offset:12528
	s_waitcnt vmcnt(0) lgkmcnt(0)
	ds_read_b128 v[4:7], v70 offset:8448
	ds_read_b128 v[94:97], v70 offset:8512
	s_waitcnt lgkmcnt(1)
	v_mfma_f32_16x16x32_bf16 v[4:7], v[4:7], v[24:27], 0
	s_waitcnt lgkmcnt(0)
	v_mfma_f32_16x16x32_bf16 v[4:7], v[94:97], v[20:23], v[4:7]
	ds_read_b128 v[94:97], v70 offset:8576
	s_waitcnt lgkmcnt(0)
	v_mfma_f32_16x16x32_bf16 v[4:7], v[94:97], v[16:19], v[4:7]
	ds_read_b128 v[94:97], v70 offset:8640
	s_waitcnt lgkmcnt(0)
	v_mfma_f32_16x16x32_bf16 v[4:7], v[94:97], v[12:15], v[4:7]
	v_mfma_f32_16x16x32_bf16 v[94:97], v[8:11], v[32:35], 0
	s_nop 7
	ds_write2_b32 v73, v94, v98 offset1:16
	ds_write2_b32 v73, v95, v99 offset0:132 offset1:148
	ds_write2_b32 v74, v96, v100 offset0:8 offset1:24
	ds_write2_b32 v74, v97, v101 offset0:140 offset1:156
	v_mfma_f32_16x16x32_bf16 v[94:97], v[8:11], v[40:43], 0
	v_mfma_f32_16x16x32_bf16 v[98:101], v[8:11], v[36:39], 0
	s_nop 7
	ds_write2_b32 v73, v94, v98 offset0:32 offset1:48
	ds_write2_b32 v73, v95, v99 offset0:164 offset1:180
	ds_write2_b32 v74, v96, v100 offset0:40 offset1:56
	ds_write2_b32 v74, v97, v101 offset0:172 offset1:188
	v_mfma_f32_16x16x32_bf16 v[94:97], v[8:11], v[48:51], 0
	v_mfma_f32_16x16x32_bf16 v[98:101], v[8:11], v[44:47], 0
	s_nop 7
	ds_write2_b32 v73, v94, v98 offset0:64 offset1:80
	ds_write2_b32 v73, v95, v99 offset0:196 offset1:212
	ds_write2_b32 v74, v96, v100 offset0:72 offset1:88
	ds_write2_b32 v74, v97, v101 offset0:204 offset1:220
	v_mfma_f32_16x16x32_bf16 v[94:97], v[8:11], v[56:59], 0
	v_mfma_f32_16x16x32_bf16 v[8:11], v[8:11], v[52:55], 0
	s_nop 7
	ds_write2_b32 v73, v94, v8 offset0:96 offset1:112
	ds_write2_b32 v73, v95, v9 offset0:228 offset1:244
	ds_write2_b32 v74, v96, v10 offset0:104 offset1:120
	ds_write2_b32 v74, v97, v11 offset0:236 offset1:252
	s_waitcnt vmcnt(0) lgkmcnt(0)
	ds_read2st64_b32 v[8:9], v75 offset1:1
	ds_read2_b32 v[140:141], v75 offset0:132 offset1:196
	ds_read2st64_b32 v[142:143], v71 offset0:4 offset1:5
	ds_read2st64_b32 v[144:145], v78 offset0:6 offset1:7
	ds_read2st64_b32 v[146:147], v79 offset0:8 offset1:9
	ds_read2st64_b32 v[148:149], v82 offset0:10 offset1:11
	ds_read2st64_b32 v[150:151], v83 offset0:12 offset1:13
	ds_read2st64_b32 v[152:153], v84 offset0:14 offset1:15
	ds_read2st64_b32 v[154:155], v85 offset0:16 offset1:17
	ds_read2st64_b32 v[156:157], v86 offset0:18 offset1:19
	ds_read2st64_b32 v[158:159], v87 offset0:20 offset1:21
	ds_read2st64_b32 v[160:161], v88 offset0:22 offset1:23
	ds_read2st64_b32 v[162:163], v89 offset0:24 offset1:25
	ds_read2st64_b32 v[164:165], v91 offset0:26 offset1:27
	ds_read2st64_b32 v[166:167], v92 offset0:28 offset1:29
	ds_read2st64_b32 v[168:169], v93 offset0:30 offset1:31
	v_mov_b32_e32 v186, v102
	v_mov_b32_e32 v187, v103
	v_mfma_f32_16x16x32_bf16 v[32:35], v[60:63], v[32:35], 0
	s_waitcnt lgkmcnt(0)
	v_pk_fma_f32 v[184:185], v[66:67], v[186:187], v[8:9] op_sel:[1,1,0] op_sel_hi:[1,0,1] neg_lo:[1,0,0]
	v_pk_fma_f32 v[188:189], v[66:67], v[186:187], v[184:185] op_sel_hi:[0,1,1]
	v_cvt_pk_bf16_f32 v190, v188, v189
	v_and_b32_e32 v191, 63, v207
	v_lshl_add_u32 v191, v191, 1, v72
	ds_write_b32 v191, v190 offset:8448
	v_pk_fma_f32 v[184:185], v[66:67], v[188:189], v[140:141] op_sel:[1,1,0] op_sel_hi:[1,0,1] neg_lo:[1,0,0]
	v_pk_fma_f32 v[186:187], v[66:67], v[188:189], v[184:185] op_sel_hi:[0,1,1]
	v_cvt_pk_bf16_f32 v190, v186, v187
	ds_write_b32 v191, v190 offset:8720
	v_pk_fma_f32 v[184:185], v[66:67], v[186:187], v[142:143] op_sel:[1,1,0] op_sel_hi:[1,0,1] neg_lo:[1,0,0]
	v_pk_fma_f32 v[188:189], v[66:67], v[186:187], v[184:185] op_sel_hi:[0,1,1]
	v_cvt_pk_bf16_f32 v190, v188, v189
	ds_write_b32 v191, v190 offset:8992
	v_pk_fma_f32 v[184:185], v[66:67], v[188:189], v[144:145] op_sel:[1,1,0] op_sel_hi:[1,0,1] neg_lo:[1,0,0]
	v_pk_fma_f32 v[186:187], v[66:67], v[188:189], v[184:185] op_sel_hi:[0,1,1]
	v_cvt_pk_bf16_f32 v190, v186, v187
	ds_write_b32 v191, v190 offset:9264
	v_pk_fma_f32 v[184:185], v[66:67], v[186:187], v[146:147] op_sel:[1,1,0] op_sel_hi:[1,0,1] neg_lo:[1,0,0]
	v_pk_fma_f32 v[188:189], v[66:67], v[186:187], v[184:185] op_sel_hi:[0,1,1]
	v_cvt_pk_bf16_f32 v190, v188, v189
	ds_write_b32 v191, v190 offset:9536
	v_pk_fma_f32 v[184:185], v[66:67], v[188:189], v[148:149] op_sel:[1,1,0] op_sel_hi:[1,0,1] neg_lo:[1,0,0]
	v_pk_fma_f32 v[186:187], v[66:67], v[188:189], v[184:185] op_sel_hi:[0,1,1]
	v_cvt_pk_bf16_f32 v190, v186, v187
	ds_write_b32 v191, v190 offset:9808
	v_pk_fma_f32 v[184:185], v[66:67], v[186:187], v[150:151] op_sel:[1,1,0] op_sel_hi:[1,0,1] neg_lo:[1,0,0]
	v_pk_fma_f32 v[188:189], v[66:67], v[186:187], v[184:185] op_sel_hi:[0,1,1]
	v_cvt_pk_bf16_f32 v190, v188, v189
	ds_write_b32 v191, v190 offset:10080
	v_pk_fma_f32 v[184:185], v[66:67], v[188:189], v[152:153] op_sel:[1,1,0] op_sel_hi:[1,0,1] neg_lo:[1,0,0]
	v_pk_fma_f32 v[186:187], v[66:67], v[188:189], v[184:185] op_sel_hi:[0,1,1]
	v_cvt_pk_bf16_f32 v190, v186, v187
	ds_write_b32 v191, v190 offset:10352
	v_pk_fma_f32 v[184:185], v[66:67], v[186:187], v[154:155] op_sel:[1,1,0] op_sel_hi:[1,0,1] neg_lo:[1,0,0]
	v_pk_fma_f32 v[188:189], v[66:67], v[186:187], v[184:185] op_sel_hi:[0,1,1]
	v_cvt_pk_bf16_f32 v190, v188, v189
	ds_write_b32 v191, v190 offset:10624
	v_pk_fma_f32 v[184:185], v[66:67], v[188:189], v[156:157] op_sel:[1,1,0] op_sel_hi:[1,0,1] neg_lo:[1,0,0]
	v_pk_fma_f32 v[186:187], v[66:67], v[188:189], v[184:185] op_sel_hi:[0,1,1]
	v_cvt_pk_bf16_f32 v190, v186, v187
	ds_write_b32 v191, v190 offset:10896
	v_pk_fma_f32 v[184:185], v[66:67], v[186:187], v[158:159] op_sel:[1,1,0] op_sel_hi:[1,0,1] neg_lo:[1,0,0]
	v_pk_fma_f32 v[188:189], v[66:67], v[186:187], v[184:185] op_sel_hi:[0,1,1]
	v_cvt_pk_bf16_f32 v190, v188, v189
	ds_write_b32 v191, v190 offset:11168
	v_pk_fma_f32 v[184:185], v[66:67], v[188:189], v[160:161] op_sel:[1,1,0] op_sel_hi:[1,0,1] neg_lo:[1,0,0]
	v_pk_fma_f32 v[186:187], v[66:67], v[188:189], v[184:185] op_sel_hi:[0,1,1]
	v_cvt_pk_bf16_f32 v190, v186, v187
	ds_write_b32 v191, v190 offset:11440
	v_pk_fma_f32 v[184:185], v[66:67], v[186:187], v[162:163] op_sel:[1,1,0] op_sel_hi:[1,0,1] neg_lo:[1,0,0]
	v_pk_fma_f32 v[188:189], v[66:67], v[186:187], v[184:185] op_sel_hi:[0,1,1]
	v_cvt_pk_bf16_f32 v190, v188, v189
	ds_write_b32 v191, v190 offset:11712
	v_pk_fma_f32 v[184:185], v[66:67], v[188:189], v[164:165] op_sel:[1,1,0] op_sel_hi:[1,0,1] neg_lo:[1,0,0]
	v_pk_fma_f32 v[186:187], v[66:67], v[188:189], v[184:185] op_sel_hi:[0,1,1]
	v_cvt_pk_bf16_f32 v190, v186, v187
	ds_write_b32 v191, v190 offset:11984
	v_pk_fma_f32 v[184:185], v[66:67], v[186:187], v[166:167] op_sel:[1,1,0] op_sel_hi:[1,0,1] neg_lo:[1,0,0]
	v_pk_fma_f32 v[188:189], v[66:67], v[186:187], v[184:185] op_sel_hi:[0,1,1]
	v_cvt_pk_bf16_f32 v190, v188, v189
	ds_write_b32 v191, v190 offset:12256
	v_pk_fma_f32 v[184:185], v[66:67], v[188:189], v[168:169] op_sel:[1,1,0] op_sel_hi:[1,0,1] neg_lo:[1,0,0]
	v_pk_fma_f32 v[186:187], v[66:67], v[188:189], v[184:185] op_sel_hi:[0,1,1]
	v_mov_b32_e32 v98, v186
	v_mov_b32_e32 v99, v187
	v_cvt_pk_bf16_f32 v190, v186, v187
	ds_write_b32 v191, v190 offset:12528
	s_waitcnt vmcnt(0) lgkmcnt(0)
	ds_read_b128 v[8:11], v70 offset:8448
	ds_read_b128 v[94:97], v70 offset:8512
	s_waitcnt lgkmcnt(1)
	v_mfma_f32_16x16x32_bf16 v[8:11], v[8:11], v[24:27], 0
	s_waitcnt lgkmcnt(0)
	v_mfma_f32_16x16x32_bf16 v[8:11], v[94:97], v[20:23], v[8:11]
	ds_read_b128 v[94:97], v70 offset:8576
	s_waitcnt lgkmcnt(0)
	v_mfma_f32_16x16x32_bf16 v[8:11], v[94:97], v[16:19], v[8:11]
	ds_read_b128 v[94:97], v70 offset:8640
	ds_write2_b32 v73, v32, v28 offset1:16
	ds_write2_b32 v73, v33, v29 offset0:132 offset1:148
	ds_write2_b32 v74, v34, v30 offset0:8 offset1:24
	ds_write2_b32 v74, v35, v31 offset0:140 offset1:156
	v_mfma_f32_16x16x32_bf16 v[28:31], v[60:63], v[40:43], 0
	v_mov_b32_e32 v40, 0
	v_mov_b32_e32 v41, 0
	v_mov_b32_e32 v42, 0
	v_mfma_f32_16x16x32_bf16 v[32:35], v[60:63], v[36:39], 0
	s_nop 7
	ds_write2_b32 v73, v28, v32 offset0:32 offset1:48
	ds_write2_b32 v73, v29, v33 offset0:164 offset1:180
	ds_write2_b32 v74, v30, v34 offset0:40 offset1:56
	ds_write2_b32 v74, v31, v35 offset0:172 offset1:188
	v_mfma_f32_16x16x32_bf16 v[28:31], v[60:63], v[48:51], 0
	v_mov_b32_e32 v36, 0
	v_mov_b32_e32 v43, 0
	v_mfma_f32_16x16x32_bf16 v[32:35], v[60:63], v[44:47], 0
	s_nop 7
	ds_write2_b32 v73, v28, v32 offset0:64 offset1:80
	ds_write2_b32 v73, v29, v33 offset0:196 offset1:212
	ds_write2_b32 v74, v30, v34 offset0:72 offset1:88
	ds_write2_b32 v74, v31, v35 offset0:204 offset1:220
	v_mfma_f32_16x16x32_bf16 v[28:31], v[60:63], v[56:59], 0
	v_mfma_f32_16x16x32_bf16 v[32:35], v[60:63], v[52:55], 0
	s_nop 7
	ds_write2_b32 v73, v28, v32 offset0:96 offset1:112
	ds_write2_b32 v73, v29, v33 offset0:228 offset1:244
	ds_write2_b32 v74, v30, v34 offset0:104 offset1:120
	ds_write2_b32 v74, v31, v35 offset0:236 offset1:252
	s_waitcnt vmcnt(0) lgkmcnt(0)
	ds_read2st64_b32 v[28:29], v75 offset1:1
	ds_read2_b32 v[140:141], v75 offset0:132 offset1:196
	ds_read2st64_b32 v[142:143], v71 offset0:4 offset1:5
	ds_read2st64_b32 v[144:145], v78 offset0:6 offset1:7
	ds_read2st64_b32 v[146:147], v79 offset0:8 offset1:9
	ds_read2st64_b32 v[148:149], v82 offset0:10 offset1:11
	ds_read2st64_b32 v[150:151], v83 offset0:12 offset1:13
	ds_read2st64_b32 v[152:153], v84 offset0:14 offset1:15
	ds_read2st64_b32 v[154:155], v85 offset0:16 offset1:17
	ds_read2st64_b32 v[156:157], v86 offset0:18 offset1:19
	ds_read2st64_b32 v[158:159], v87 offset0:20 offset1:21
	ds_read2st64_b32 v[160:161], v88 offset0:22 offset1:23
	ds_read2st64_b32 v[162:163], v89 offset0:24 offset1:25
	ds_read2st64_b32 v[164:165], v91 offset0:26 offset1:27
	ds_read2st64_b32 v[166:167], v92 offset0:28 offset1:29
	ds_read2st64_b32 v[168:169], v93 offset0:30 offset1:31
	v_mov_b32_e32 v186, v98
	v_mov_b32_e32 v187, v99
	s_waitcnt lgkmcnt(0)
	v_mfma_f32_16x16x32_bf16 v[8:11], v[94:97], v[12:15], v[8:11]
	v_pk_fma_f32 v[184:185], v[66:67], v[186:187], v[28:29] op_sel:[1,1,0] op_sel_hi:[1,0,1] neg_lo:[1,0,0]
	v_pk_fma_f32 v[188:189], v[66:67], v[186:187], v[184:185] op_sel_hi:[0,1,1]
	v_cvt_pk_bf16_f32 v190, v188, v189
	v_and_b32_e32 v191, 63, v207
	v_lshl_add_u32 v191, v191, 1, v72
	ds_write_b32 v191, v190 offset:8448
	v_pk_fma_f32 v[184:185], v[66:67], v[188:189], v[140:141] op_sel:[1,1,0] op_sel_hi:[1,0,1] neg_lo:[1,0,0]
	v_pk_fma_f32 v[186:187], v[66:67], v[188:189], v[184:185] op_sel_hi:[0,1,1]
	v_cvt_pk_bf16_f32 v190, v186, v187
	ds_write_b32 v191, v190 offset:8720
	v_pk_fma_f32 v[184:185], v[66:67], v[186:187], v[142:143] op_sel:[1,1,0] op_sel_hi:[1,0,1] neg_lo:[1,0,0]
	v_pk_fma_f32 v[188:189], v[66:67], v[186:187], v[184:185] op_sel_hi:[0,1,1]
	v_cvt_pk_bf16_f32 v190, v188, v189
	ds_write_b32 v191, v190 offset:8992
	v_pk_fma_f32 v[184:185], v[66:67], v[188:189], v[144:145] op_sel:[1,1,0] op_sel_hi:[1,0,1] neg_lo:[1,0,0]
	v_pk_fma_f32 v[186:187], v[66:67], v[188:189], v[184:185] op_sel_hi:[0,1,1]
	v_cvt_pk_bf16_f32 v190, v186, v187
	ds_write_b32 v191, v190 offset:9264
	v_pk_fma_f32 v[184:185], v[66:67], v[186:187], v[146:147] op_sel:[1,1,0] op_sel_hi:[1,0,1] neg_lo:[1,0,0]
	v_pk_fma_f32 v[188:189], v[66:67], v[186:187], v[184:185] op_sel_hi:[0,1,1]
	v_cvt_pk_bf16_f32 v190, v188, v189
	ds_write_b32 v191, v190 offset:9536
	v_pk_fma_f32 v[184:185], v[66:67], v[188:189], v[148:149] op_sel:[1,1,0] op_sel_hi:[1,0,1] neg_lo:[1,0,0]
	v_pk_fma_f32 v[186:187], v[66:67], v[188:189], v[184:185] op_sel_hi:[0,1,1]
	v_cvt_pk_bf16_f32 v190, v186, v187
	ds_write_b32 v191, v190 offset:9808
	v_pk_fma_f32 v[184:185], v[66:67], v[186:187], v[150:151] op_sel:[1,1,0] op_sel_hi:[1,0,1] neg_lo:[1,0,0]
	v_pk_fma_f32 v[188:189], v[66:67], v[186:187], v[184:185] op_sel_hi:[0,1,1]
	v_cvt_pk_bf16_f32 v190, v188, v189
	ds_write_b32 v191, v190 offset:10080
	v_pk_fma_f32 v[184:185], v[66:67], v[188:189], v[152:153] op_sel:[1,1,0] op_sel_hi:[1,0,1] neg_lo:[1,0,0]
	v_pk_fma_f32 v[186:187], v[66:67], v[188:189], v[184:185] op_sel_hi:[0,1,1]
	v_cvt_pk_bf16_f32 v190, v186, v187
	ds_write_b32 v191, v190 offset:10352
	v_pk_fma_f32 v[184:185], v[66:67], v[186:187], v[154:155] op_sel:[1,1,0] op_sel_hi:[1,0,1] neg_lo:[1,0,0]
	v_pk_fma_f32 v[188:189], v[66:67], v[186:187], v[184:185] op_sel_hi:[0,1,1]
	v_cvt_pk_bf16_f32 v190, v188, v189
	ds_write_b32 v191, v190 offset:10624
	v_pk_fma_f32 v[184:185], v[66:67], v[188:189], v[156:157] op_sel:[1,1,0] op_sel_hi:[1,0,1] neg_lo:[1,0,0]
	v_pk_fma_f32 v[186:187], v[66:67], v[188:189], v[184:185] op_sel_hi:[0,1,1]
	v_cvt_pk_bf16_f32 v190, v186, v187
	ds_write_b32 v191, v190 offset:10896
	v_pk_fma_f32 v[184:185], v[66:67], v[186:187], v[158:159] op_sel:[1,1,0] op_sel_hi:[1,0,1] neg_lo:[1,0,0]
	v_pk_fma_f32 v[188:189], v[66:67], v[186:187], v[184:185] op_sel_hi:[0,1,1]
	v_cvt_pk_bf16_f32 v190, v188, v189
	ds_write_b32 v191, v190 offset:11168
	v_pk_fma_f32 v[184:185], v[66:67], v[188:189], v[160:161] op_sel:[1,1,0] op_sel_hi:[1,0,1] neg_lo:[1,0,0]
	v_pk_fma_f32 v[186:187], v[66:67], v[188:189], v[184:185] op_sel_hi:[0,1,1]
	v_cvt_pk_bf16_f32 v190, v186, v187
	ds_write_b32 v191, v190 offset:11440
	v_pk_fma_f32 v[184:185], v[66:67], v[186:187], v[162:163] op_sel:[1,1,0] op_sel_hi:[1,0,1] neg_lo:[1,0,0]
	v_pk_fma_f32 v[188:189], v[66:67], v[186:187], v[184:185] op_sel_hi:[0,1,1]
	v_cvt_pk_bf16_f32 v190, v188, v189
	ds_write_b32 v191, v190 offset:11712
	v_pk_fma_f32 v[184:185], v[66:67], v[188:189], v[164:165] op_sel:[1,1,0] op_sel_hi:[1,0,1] neg_lo:[1,0,0]
	v_pk_fma_f32 v[186:187], v[66:67], v[188:189], v[184:185] op_sel_hi:[0,1,1]
	v_cvt_pk_bf16_f32 v190, v186, v187
	ds_write_b32 v191, v190 offset:11984
	v_pk_fma_f32 v[184:185], v[66:67], v[186:187], v[166:167] op_sel:[1,1,0] op_sel_hi:[1,0,1] neg_lo:[1,0,0]
	v_pk_fma_f32 v[188:189], v[66:67], v[186:187], v[184:185] op_sel_hi:[0,1,1]
	v_cvt_pk_bf16_f32 v190, v188, v189
	ds_write_b32 v191, v190 offset:12256
	v_pk_fma_f32 v[184:185], v[66:67], v[188:189], v[168:169] op_sel:[1,1,0] op_sel_hi:[1,0,1] neg_lo:[1,0,0]
	v_pk_fma_f32 v[186:187], v[66:67], v[188:189], v[184:185] op_sel_hi:[0,1,1]
	v_mov_b32_e32 v28, v186
	v_mov_b32_e32 v29, v187
	v_cvt_pk_bf16_f32 v190, v186, v187
	ds_write_b32 v191, v190 offset:12528
	s_waitcnt vmcnt(0) lgkmcnt(0)
	ds_read_b128 v[28:31], v70 offset:8448
	s_waitcnt lgkmcnt(0)
	v_mfma_f32_16x16x32_bf16 v[24:27], v[28:31], v[24:27], 0
	ds_read_b128 v[28:31], v70 offset:8512
	s_add_u32 s0, s0, s1
	s_addc_u32 s1, s2, 0
	s_waitcnt lgkmcnt(0)
	v_mfma_f32_16x16x32_bf16 v[20:23], v[28:31], v[20:23], v[24:27]
	s_nop 2
	ds_read_b128 v[24:27], v70 offset:8576
	s_lshl_b64 s[0:1], s[0:1], 14
	s_waitcnt lgkmcnt(0)
	v_mfma_f32_16x16x32_bf16 v[16:19], v[24:27], v[16:19], v[20:23]
	s_nop 2
	ds_read_b128 v[20:23], v70 offset:8640
	s_waitcnt lgkmcnt(0)
	v_mfma_f32_16x16x32_bf16 v[12:15], v[20:23], v[12:15], v[16:19]
	s_nop 2
	v_lshl_add_u64 v[16:17], v[64:65], 0, s[0:1]
	v_mov_b32_e32 v20, v207
	global_load_dwordx2 v[84:85], v[16:17], off
	v_add_u32_e32 v16, s90, v77
	v_and_b32_e32 v91, 63, v20
	v_or_b32_e32 v16, v91, v16
	v_ashrrev_i32_e32 v17, 31, v16
	v_lshl_add_u64 v[16:17], v[16:17], 3, s[60:61]
	global_load_dwordx2 v[82:83], v[16:17], off
	v_add_u32_e32 v16, s91, v76
	v_ashrrev_i32_e32 v17, 31, v16
	v_and_b32_e32 v92, 15, v20
	v_lshlrev_b64 v[16:17], 12, v[16:17]
	v_lshl_add_u64 v[18:19], s[62:63], 0, v[16:17]
	v_lshlrev_b32_e32 v21, 4, v92
	v_and_b32_e32 v128, 48, v20
	v_cmp_gt_u32_e64 s[42:43], 32, v91
	v_lshl_add_u64 v[18:19], v[18:19], 0, v[128:129]
	v_lshlrev_b32_e32 v128, 1, v21
	s_and_saveexec_b64 s[0:1], s[42:43]
	s_cbranch_execz .LBB0_1789
	v_lshl_add_u64 v[22:23], v[18:19], 0, v[128:129]
	global_load_dwordx4 v[40:43], v[22:23], off

.LBB0_1803:
	s_or_b64 exec, exec, s[0:1]
	v_bfe_u32 v93, v20, 4, 2
	v_lshlrev_b32_e32 v18, 3, v93
	v_lshl_add_u64 v[16:17], s[46:47], 0, v[16:17]
	v_lshlrev_b32_e32 v128, 8, v92
	v_lshl_add_u64 v[16:17], v[16:17], 0, v[128:129]
	v_mov_b32_e32 v156, v18
	v_mov_b32_e32 v157, 0
	v_lshl_add_u64 v[156:157], v[16:17], 0, v[156:157]
	v_lshlrev_b32_e32 v128, 1, v18
	v_lshl_add_u64 v[16:17], v[16:17], 0, v[128:129]
	global_load_dwordx2 v[140:141], v[156:157], off
	global_load_dwordx2 v[142:143], v[156:157], off offset:128
	global_load_dwordx2 v[144:145], v[156:157], off offset:32
	global_load_dwordx2 v[146:147], v[156:157], off offset:160
	global_load_dwordx2 v[148:149], v[156:157], off offset:64
	global_load_dwordx2 v[150:151], v[156:157], off offset:192
	global_load_dwordx2 v[152:153], v[156:157], off offset:96
	global_load_dwordx2 v[154:155], v[156:157], off offset:224
	v_add_u32_e32 v88, s8, v92
	v_lshl_add_u64 v[86:87], v[68:69], 0, v[128:129]
	v_mov_b32_e32 v76, 0
	v_ashrrev_i32_e32 v89, 31, v88
	v_mov_b32_e32 v68, 0
	v_mov_b32_e32 v69, 0
	v_mov_b32_e32 v70, 0
	v_mov_b32_e32 v71, 0
	s_and_saveexec_b64 s[0:1], s[42:43]
	s_cbranch_execz .LBB0_1805
	v_lshlrev_b64 v[16:17], 10, v[88:89]
	v_lshl_add_u64 v[16:17], v[86:87], 0, v[16:17]
	global_load_dwordx4 v[68:71], v[16:17], off

.LBB0_1811:
	s_or_b64 exec, exec, s[0:1]
	s_waitcnt vmcnt(0) lgkmcnt(0)
	v_mov_b32_e32 v158, 0x5040100
	v_mov_b32_e32 v159, 0x7060302
	v_perm_b32 v32, v142, v140, v158
	v_perm_b32 v33, v142, v140, v159
	v_perm_b32 v34, v143, v141, v158
	v_perm_b32 v35, v143, v141, v159
	v_perm_b32 v28, v146, v144, v158
	v_perm_b32 v29, v146, v144, v159
	v_perm_b32 v30, v147, v145, v158
	v_perm_b32 v31, v147, v145, v159
	v_perm_b32 v24, v150, v148, v158
	v_perm_b32 v25, v150, v148, v159
	v_perm_b32 v26, v151, v149, v158
	v_perm_b32 v27, v151, v149, v159
	v_perm_b32 v20, v154, v152, v158
	v_perm_b32 v21, v154, v152, v159
	v_perm_b32 v22, v155, v153, v158
	v_perm_b32 v23, v155, v153, v159
	v_mfma_f32_16x16x32_bf16 v[94:97], v[16:19], v[40:43], 0
	v_mul_u32_u24_e32 v86, 0x210, v93
	v_lshlrev_b32_e32 v87, 2, v92
	v_lshlrev_b32_e32 v86, 2, v86
	v_mfma_f32_16x16x32_bf16 v[98:101], v[16:19], v[36:39], 0
	v_add3_u32 v88, v81, v87, v86
	v_add_u32_e32 v89, 0x400, v88
	v_mul_u32_u24_e32 v103, 0x110, v92
	s_nop 4
	ds_write2_b32 v88, v94, v98 offset1:16
	ds_write2_b32 v88, v95, v99 offset0:132 offset1:148
	ds_write2_b32 v89, v96, v100 offset0:8 offset1:24
	ds_write2_b32 v89, v97, v101 offset0:140 offset1:156
	v_mfma_f32_16x16x32_bf16 v[92:95], v[16:19], v[48:51], 0
	v_lshl_add_u32 v87, v91, 2, v81
	v_add3_u32 v81, v81, v128, v103
	v_pk_add_f32 v[0:1], v[0:1], 0 op_sel_hi:[1,0]
	v_mfma_f32_16x16x32_bf16 v[96:99], v[16:19], v[44:47], 0
	s_nop 7
	ds_write2_b32 v88, v92, v96 offset0:32 offset1:48
	ds_write2_b32 v88, v93, v97 offset0:164 offset1:180
	ds_write2_b32 v89, v94, v98 offset0:40 offset1:56
	ds_write2_b32 v89, v95, v99 offset0:172 offset1:188
	v_mfma_f32_16x16x32_bf16 v[92:95], v[16:19], v[56:59], 0
	v_readlane_b32 s68, v251, 41
	v_readlane_b32 s76, v251, 49
	v_readlane_b32 s77, v251, 50
	v_mfma_f32_16x16x32_bf16 v[96:99], v[16:19], v[52:55], 0
	s_nop 7
	ds_write2_b32 v88, v92, v96 offset0:64 offset1:80
	ds_write2_b32 v88, v93, v97 offset0:196 offset1:212
	ds_write2_b32 v89, v94, v98 offset0:72 offset1:88
	ds_write2_b32 v89, v95, v99 offset0:204 offset1:220
	v_mfma_f32_16x16x32_bf16 v[92:95], v[16:19], v[64:67], 0
	s_mov_b32 s10, 0x3f200000
	v_readlane_b32 s69, v251, 42
	v_readlane_b32 s70, v251, 43
	v_mfma_f32_16x16x32_bf16 v[16:19], v[16:19], v[60:63], 0
	s_nop 7
	ds_write2_b32 v88, v92, v16 offset0:96 offset1:112
	ds_write2_b32 v88, v93, v17 offset0:228 offset1:244
	ds_write2_b32 v89, v94, v18 offset0:104 offset1:120
	ds_write2_b32 v89, v95, v19 offset0:236 offset1:252
	v_lshlrev_b32_e32 v16, 1, v91
	v_add_u32_e32 v91, 0xf0, v87
	s_waitcnt vmcnt(0) lgkmcnt(0)
	v_sub_u32_e32 v86, v87, v16
	ds_read2st64_b32 v[16:17], v91 offset0:30 offset1:31
	v_add_u32_e32 v140, 0xe0, v87
	ds_read2st64_b32 v[142:143], v140 offset0:28 offset1:29
	v_add_u32_e32 v141, 0xd0, v87
	ds_read2st64_b32 v[144:145], v141 offset0:26 offset1:27
	v_add_u32_e32 v146, 0xc0, v87
	ds_read2st64_b32 v[148:149], v146 offset0:24 offset1:25
	v_add_u32_e32 v147, 0xb0, v87
	ds_read2st64_b32 v[150:151], v147 offset0:22 offset1:23
	v_add_u32_e32 v152, 0xa0, v87
	ds_read2st64_b32 v[154:155], v152 offset0:20 offset1:21
	v_add_u32_e32 v153, 0x90, v87
	ds_read2st64_b32 v[156:157], v153 offset0:18 offset1:19
	v_add_u32_e32 v158, 0x80, v87
	ds_read2st64_b32 v[160:161], v158 offset0:16 offset1:17
	v_add_u32_e32 v159, 0x70, v87
	ds_read2st64_b32 v[162:163], v159 offset0:14 offset1:15
	v_add_u32_e32 v164, 0x60, v87
	ds_read2st64_b32 v[166:167], v164 offset0:12 offset1:13
	v_add_u32_e32 v165, 0x50, v87
	ds_read2st64_b32 v[168:169], v165 offset0:10 offset1:11
	v_add_u32_e32 v170, 64, v87
	ds_read2st64_b32 v[172:173], v170 offset0:8 offset1:9
	v_add_u32_e32 v171, 48, v87
	ds_read2st64_b32 v[174:175], v171 offset0:6 offset1:7
	v_add_u32_e32 v176, 32, v87
	ds_read2st64_b32 v[178:179], v176 offset0:4 offset1:5
	ds_read2_b32 v[180:181], v87 offset0:132 offset1:196
	ds_read2st64_b32 v[182:183], v87 offset1:1
	v_mov_b32_e32 v186, v84
	v_mov_b32_e32 v187, v85
	v_mfma_f32_16x16x32_bf16 v[108:111], v[72:75], v[36:39], 0
	v_readlane_b32 s71, v251, 44
	s_waitcnt lgkmcnt(0)
	v_pk_fma_f32 v[184:185], v[82:83], v[186:187], v[16:17] op_sel:[1,1,0] op_sel_hi:[1,0,1] neg_lo:[1,0,0]
	v_pk_fma_f32 v[188:189], v[82:83], v[186:187], v[184:185] op_sel_hi:[0,1,1]
	v_cvt_pk_bf16_f32 v190, v188, v189
	v_and_b32_e32 v191, 63, v207
	v_lshl_add_u32 v191, v191, 1, v86
	ds_write_b32 v191, v190 offset:12528
	v_add_u32_e32 v84, 0xe0, v87
	v_readlane_b32 s72, v251, 45
	v_readlane_b32 s73, v251, 46
	v_pk_fma_f32 v[184:185], v[82:83], v[188:189], v[142:143] op_sel:[1,1,0] op_sel_hi:[1,0,1] neg_lo:[1,0,0]
	v_pk_fma_f32 v[186:187], v[82:83], v[188:189], v[184:185] op_sel_hi:[0,1,1]
	v_cvt_pk_bf16_f32 v190, v186, v187
	ds_write_b32 v191, v190 offset:12256
	v_add_u32_e32 v85, 0xd0, v87
	v_readlane_b32 s74, v251, 47
	v_readlane_b32 s75, v251, 48
	v_pk_fma_f32 v[184:185], v[82:83], v[186:187], v[144:145] op_sel:[1,1,0] op_sel_hi:[1,0,1] neg_lo:[1,0,0]
	v_pk_fma_f32 v[188:189], v[82:83], v[186:187], v[184:185] op_sel_hi:[0,1,1]
	v_cvt_pk_bf16_f32 v190, v188, v189
	ds_write_b32 v191, v190 offset:11984
	v_add_u32_e32 v92, 0xc0, v87
	v_readlane_b32 s78, v251, 51
	v_readlane_b32 s79, v251, 52
	v_pk_fma_f32 v[184:185], v[82:83], v[188:189], v[148:149] op_sel:[1,1,0] op_sel_hi:[1,0,1] neg_lo:[1,0,0]
	v_pk_fma_f32 v[186:187], v[82:83], v[188:189], v[184:185] op_sel_hi:[0,1,1]
	v_cvt_pk_bf16_f32 v190, v186, v187
	ds_write_b32 v191, v190 offset:11712
	v_add_u32_e32 v93, 0xb0, v87
	v_readlane_b32 s80, v251, 53
	v_readlane_b32 s81, v251, 54
	v_pk_fma_f32 v[184:185], v[82:83], v[186:187], v[150:151] op_sel:[1,1,0] op_sel_hi:[1,0,1] neg_lo:[1,0,0]
	v_pk_fma_f32 v[188:189], v[82:83], v[186:187], v[184:185] op_sel_hi:[0,1,1]
	v_cvt_pk_bf16_f32 v190, v188, v189
	ds_write_b32 v191, v190 offset:11440
	v_add_u32_e32 v94, 0xa0, v87
	v_readlane_b32 s82, v251, 55
	v_readlane_b32 s83, v251, 56
	v_pk_fma_f32 v[184:185], v[82:83], v[188:189], v[154:155] op_sel:[1,1,0] op_sel_hi:[1,0,1] neg_lo:[1,0,0]
	v_pk_fma_f32 v[186:187], v[82:83], v[188:189], v[184:185] op_sel_hi:[0,1,1]
	v_cvt_pk_bf16_f32 v190, v186, v187
	ds_write_b32 v191, v190 offset:11168
	v_add_u32_e32 v95, 0x90, v87
	v_pk_fma_f32 v[184:185], v[82:83], v[186:187], v[156:157] op_sel:[1,1,0] op_sel_hi:[1,0,1] neg_lo:[1,0,0]
	v_pk_fma_f32 v[188:189], v[82:83], v[186:187], v[184:185] op_sel_hi:[0,1,1]
	v_cvt_pk_bf16_f32 v190, v188, v189
	ds_write_b32 v191, v190 offset:10896
	v_add_u32_e32 v96, 0x80, v87
	v_pk_fma_f32 v[184:185], v[82:83], v[188:189], v[160:161] op_sel:[1,1,0] op_sel_hi:[1,0,1] neg_lo:[1,0,0]
	v_pk_fma_f32 v[186:187], v[82:83], v[188:189], v[184:185] op_sel_hi:[0,1,1]
	v_cvt_pk_bf16_f32 v190, v186, v187
	ds_write_b32 v191, v190 offset:10624
	v_add_u32_e32 v97, 0x70, v87
	v_pk_fma_f32 v[184:185], v[82:83], v[186:187], v[162:163] op_sel:[1,1,0] op_sel_hi:[1,0,1] neg_lo:[1,0,0]
	v_pk_fma_f32 v[188:189], v[82:83], v[186:187], v[184:185] op_sel_hi:[0,1,1]
	v_cvt_pk_bf16_f32 v190, v188, v189
	ds_write_b32 v191, v190 offset:10352
	v_add_u32_e32 v98, 0x60, v87
	v_pk_fma_f32 v[184:185], v[82:83], v[188:189], v[166:167] op_sel:[1,1,0] op_sel_hi:[1,0,1] neg_lo:[1,0,0]
	v_pk_fma_f32 v[186:187], v[82:83], v[188:189], v[184:185] op_sel_hi:[0,1,1]
	v_cvt_pk_bf16_f32 v190, v186, v187
	ds_write_b32 v191, v190 offset:10080
	v_add_u32_e32 v99, 0x50, v87
	v_pk_fma_f32 v[184:185], v[82:83], v[186:187], v[168:169] op_sel:[1,1,0] op_sel_hi:[1,0,1] neg_lo:[1,0,0]
	v_pk_fma_f32 v[188:189], v[82:83], v[186:187], v[184:185] op_sel_hi:[0,1,1]
	v_cvt_pk_bf16_f32 v190, v188, v189
	ds_write_b32 v191, v190 offset:9808
	v_add_u32_e32 v100, 64, v87
	v_pk_fma_f32 v[184:185], v[82:83], v[188:189], v[172:173] op_sel:[1,1,0] op_sel_hi:[1,0,1] neg_lo:[1,0,0]
	v_pk_fma_f32 v[186:187], v[82:83], v[188:189], v[184:185] op_sel_hi:[0,1,1]
	v_cvt_pk_bf16_f32 v190, v186, v187
	ds_write_b32 v191, v190 offset:9536
	v_add_u32_e32 v101, 48, v87
	v_pk_fma_f32 v[184:185], v[82:83], v[186:187], v[174:175] op_sel:[1,1,0] op_sel_hi:[1,0,1] neg_lo:[1,0,0]
	v_pk_fma_f32 v[188:189], v[82:83], v[186:187], v[184:185] op_sel_hi:[0,1,1]
	v_cvt_pk_bf16_f32 v190, v188, v189
	ds_write_b32 v191, v190 offset:9264
	v_add_u32_e32 v102, 32, v87
	v_pk_fma_f32 v[184:185], v[82:83], v[188:189], v[178:179] op_sel:[1,1,0] op_sel_hi:[1,0,1] neg_lo:[1,0,0]
	v_pk_fma_f32 v[186:187], v[82:83], v[188:189], v[184:185] op_sel_hi:[0,1,1]
	v_cvt_pk_bf16_f32 v190, v186, v187
	ds_write_b32 v191, v190 offset:8992
	v_pk_fma_f32 v[184:185], v[82:83], v[186:187], v[180:181] op_sel:[1,1,0] op_sel_hi:[1,0,1] neg_lo:[1,0,0]
	v_pk_fma_f32 v[188:189], v[82:83], v[186:187], v[184:185] op_sel_hi:[0,1,1]
	v_cvt_pk_bf16_f32 v190, v188, v189
	ds_write_b32 v191, v190 offset:8720
	v_pk_fma_f32 v[184:185], v[82:83], v[188:189], v[182:183] op_sel:[1,1,0] op_sel_hi:[1,0,1] neg_lo:[1,0,0]
	v_pk_fma_f32 v[186:187], v[82:83], v[188:189], v[184:185] op_sel_hi:[0,1,1]
	v_mov_b32_e32 v112, v186
	v_mov_b32_e32 v113, v187
	v_cvt_pk_bf16_f32 v190, v186, v187
	ds_write_b32 v191, v190 offset:8448
	s_waitcnt vmcnt(0) lgkmcnt(0)
	ds_read_b128 v[16:19], v81 offset:8448
	ds_read_b128 v[104:107], v81 offset:8512
	s_waitcnt lgkmcnt(1)
	v_mfma_f32_16x16x32_bf16 v[16:19], v[16:19], v[32:35], 0
	s_waitcnt lgkmcnt(0)
	v_mfma_f32_16x16x32_bf16 v[16:19], v[104:107], v[28:31], v[16:19]
	ds_read_b128 v[104:107], v81 offset:8576
	s_waitcnt lgkmcnt(0)
	v_mfma_f32_16x16x32_bf16 v[16:19], v[104:107], v[24:27], v[16:19]
	ds_read_b128 v[104:107], v81 offset:8640
	s_waitcnt lgkmcnt(0)
	v_mfma_f32_16x16x32_bf16 v[16:19], v[104:107], v[20:23], v[16:19]
	v_mfma_f32_16x16x32_bf16 v[104:107], v[72:75], v[40:43], 0
	s_nop 7
	ds_write2_b32 v88, v104, v108 offset1:16
	ds_write2_b32 v88, v105, v109 offset0:132 offset1:148
	ds_write2_b32 v89, v106, v110 offset0:8 offset1:24
	ds_write2_b32 v89, v107, v111 offset0:140 offset1:156
	v_mfma_f32_16x16x32_bf16 v[104:107], v[72:75], v[48:51], 0
	v_mfma_f32_16x16x32_bf16 v[108:111], v[72:75], v[44:47], 0
	s_nop 7
	ds_write2_b32 v88, v104, v108 offset0:32 offset1:48
	ds_write2_b32 v88, v105, v109 offset0:164 offset1:180
	ds_write2_b32 v89, v106, v110 offset0:40 offset1:56
	ds_write2_b32 v89, v107, v111 offset0:172 offset1:188
	v_mfma_f32_16x16x32_bf16 v[104:107], v[72:75], v[56:59], 0
	v_mfma_f32_16x16x32_bf16 v[108:111], v[72:75], v[52:55], 0
	s_nop 7
	ds_write2_b32 v88, v104, v108 offset0:64 offset1:80
	ds_write2_b32 v88, v105, v109 offset0:196 offset1:212
	ds_write2_b32 v89, v106, v110 offset0:72 offset1:88
	ds_write2_b32 v89, v107, v111 offset0:204 offset1:220
	v_mfma_f32_16x16x32_bf16 v[104:107], v[72:75], v[64:67], 0
	v_mfma_f32_16x16x32_bf16 v[72:75], v[72:75], v[60:63], 0
	s_nop 7
	ds_write2_b32 v88, v104, v72 offset0:96 offset1:112
	ds_write2_b32 v88, v105, v73 offset0:228 offset1:244
	ds_write2_b32 v89, v106, v74 offset0:104 offset1:120
	ds_write2_b32 v89, v107, v75 offset0:236 offset1:252
	s_waitcnt vmcnt(0) lgkmcnt(0)
	ds_read2st64_b32 v[72:73], v91 offset0:30 offset1:31
	ds_read2st64_b32 v[140:141], v84 offset0:28 offset1:29
	ds_read2st64_b32 v[142:143], v85 offset0:26 offset1:27
	ds_read2st64_b32 v[144:145], v92 offset0:24 offset1:25
	ds_read2st64_b32 v[146:147], v93 offset0:22 offset1:23
	ds_read2st64_b32 v[148:149], v94 offset0:20 offset1:21
	ds_read2st64_b32 v[150:151], v95 offset0:18 offset1:19
	ds_read2st64_b32 v[152:153], v96 offset0:16 offset1:17
	ds_read2st64_b32 v[154:155], v97 offset0:14 offset1:15
	ds_read2st64_b32 v[156:157], v98 offset0:12 offset1:13
	ds_read2st64_b32 v[158:159], v99 offset0:10 offset1:11
	ds_read2st64_b32 v[160:161], v100 offset0:8 offset1:9
	ds_read2st64_b32 v[162:163], v101 offset0:6 offset1:7
	ds_read2st64_b32 v[164:165], v102 offset0:4 offset1:5
	ds_read2_b32 v[166:167], v87 offset0:132 offset1:196
	ds_read2st64_b32 v[168:169], v87 offset1:1
	v_mov_b32_e32 v186, v112
	v_mov_b32_e32 v187, v113
	v_mfma_f32_16x16x32_bf16 v[108:111], v[76:79], v[36:39], 0
	s_waitcnt lgkmcnt(0)
	v_pk_fma_f32 v[184:185], v[82:83], v[186:187], v[72:73] op_sel:[1,1,0] op_sel_hi:[1,0,1] neg_lo:[1,0,0]
	v_pk_fma_f32 v[188:189], v[82:83], v[186:187], v[184:185] op_sel_hi:[0,1,1]
	v_cvt_pk_bf16_f32 v190, v188, v189
	v_and_b32_e32 v191, 63, v207
	v_lshl_add_u32 v191, v191, 1, v86
	ds_write_b32 v191, v190 offset:12528
	v_mfma_f32_16x16x32_bf16 v[36:39], v[68:71], v[36:39], 0
	v_pk_fma_f32 v[184:185], v[82:83], v[188:189], v[140:141] op_sel:[1,1,0] op_sel_hi:[1,0,1] neg_lo:[1,0,0]
	v_pk_fma_f32 v[186:187], v[82:83], v[188:189], v[184:185] op_sel_hi:[0,1,1]
	v_cvt_pk_bf16_f32 v190, v186, v187
	ds_write_b32 v191, v190 offset:12256
	v_pk_fma_f32 v[184:185], v[82:83], v[186:187], v[142:143] op_sel:[1,1,0] op_sel_hi:[1,0,1] neg_lo:[1,0,0]
	v_pk_fma_f32 v[188:189], v[82:83], v[186:187], v[184:185] op_sel_hi:[0,1,1]
	v_cvt_pk_bf16_f32 v190, v188, v189
	ds_write_b32 v191, v190 offset:11984
	v_pk_fma_f32 v[184:185], v[82:83], v[188:189], v[144:145] op_sel:[1,1,0] op_sel_hi:[1,0,1] neg_lo:[1,0,0]
	v_pk_fma_f32 v[186:187], v[82:83], v[188:189], v[184:185] op_sel_hi:[0,1,1]
	v_cvt_pk_bf16_f32 v190, v186, v187
	ds_write_b32 v191, v190 offset:11712
	v_pk_fma_f32 v[184:185], v[82:83], v[186:187], v[146:147] op_sel:[1,1,0] op_sel_hi:[1,0,1] neg_lo:[1,0,0]
	v_pk_fma_f32 v[188:189], v[82:83], v[186:187], v[184:185] op_sel_hi:[0,1,1]
	v_cvt_pk_bf16_f32 v190, v188, v189
	ds_write_b32 v191, v190 offset:11440
	v_pk_fma_f32 v[184:185], v[82:83], v[188:189], v[148:149] op_sel:[1,1,0] op_sel_hi:[1,0,1] neg_lo:[1,0,0]
	v_pk_fma_f32 v[186:187], v[82:83], v[188:189], v[184:185] op_sel_hi:[0,1,1]
	v_cvt_pk_bf16_f32 v190, v186, v187
	ds_write_b32 v191, v190 offset:11168
	v_pk_fma_f32 v[184:185], v[82:83], v[186:187], v[150:151] op_sel:[1,1,0] op_sel_hi:[1,0,1] neg_lo:[1,0,0]
	v_pk_fma_f32 v[188:189], v[82:83], v[186:187], v[184:185] op_sel_hi:[0,1,1]
	v_cvt_pk_bf16_f32 v190, v188, v189
	ds_write_b32 v191, v190 offset:10896
	v_pk_fma_f32 v[184:185], v[82:83], v[188:189], v[152:153] op_sel:[1,1,0] op_sel_hi:[1,0,1] neg_lo:[1,0,0]
	v_pk_fma_f32 v[186:187], v[82:83], v[188:189], v[184:185] op_sel_hi:[0,1,1]
	v_cvt_pk_bf16_f32 v190, v186, v187
	ds_write_b32 v191, v190 offset:10624
	v_pk_fma_f32 v[184:185], v[82:83], v[186:187], v[154:155] op_sel:[1,1,0] op_sel_hi:[1,0,1] neg_lo:[1,0,0]
	v_pk_fma_f32 v[188:189], v[82:83], v[186:187], v[184:185] op_sel_hi:[0,1,1]
	v_cvt_pk_bf16_f32 v190, v188, v189
	ds_write_b32 v191, v190 offset:10352
	v_pk_fma_f32 v[184:185], v[82:83], v[188:189], v[156:157] op_sel:[1,1,0] op_sel_hi:[1,0,1] neg_lo:[1,0,0]
	v_pk_fma_f32 v[186:187], v[82:83], v[188:189], v[184:185] op_sel_hi:[0,1,1]
	v_cvt_pk_bf16_f32 v190, v186, v187
	ds_write_b32 v191, v190 offset:10080
	v_pk_fma_f32 v[184:185], v[82:83], v[186:187], v[158:159] op_sel:[1,1,0] op_sel_hi:[1,0,1] neg_lo:[1,0,0]
	v_pk_fma_f32 v[188:189], v[82:83], v[186:187], v[184:185] op_sel_hi:[0,1,1]
	v_cvt_pk_bf16_f32 v190, v188, v189
	ds_write_b32 v191, v190 offset:9808
	v_pk_fma_f32 v[184:185], v[82:83], v[188:189], v[160:161] op_sel:[1,1,0] op_sel_hi:[1,0,1] neg_lo:[1,0,0]
	v_pk_fma_f32 v[186:187], v[82:83], v[188:189], v[184:185] op_sel_hi:[0,1,1]
	v_cvt_pk_bf16_f32 v190, v186, v187
	ds_write_b32 v191, v190 offset:9536
	v_pk_fma_f32 v[184:185], v[82:83], v[186:187], v[162:163] op_sel:[1,1,0] op_sel_hi:[1,0,1] neg_lo:[1,0,0]
	v_pk_fma_f32 v[188:189], v[82:83], v[186:187], v[184:185] op_sel_hi:[0,1,1]
	v_cvt_pk_bf16_f32 v190, v188, v189
	ds_write_b32 v191, v190 offset:9264
	v_pk_fma_f32 v[184:185], v[82:83], v[188:189], v[164:165] op_sel:[1,1,0] op_sel_hi:[1,0,1] neg_lo:[1,0,0]
	v_pk_fma_f32 v[186:187], v[82:83], v[188:189], v[184:185] op_sel_hi:[0,1,1]
	v_cvt_pk_bf16_f32 v190, v186, v187
	ds_write_b32 v191, v190 offset:8992
	v_pk_fma_f32 v[184:185], v[82:83], v[186:187], v[166:167] op_sel:[1,1,0] op_sel_hi:[1,0,1] neg_lo:[1,0,0]
	v_pk_fma_f32 v[188:189], v[82:83], v[186:187], v[184:185] op_sel_hi:[0,1,1]
	v_cvt_pk_bf16_f32 v190, v188, v189
	ds_write_b32 v191, v190 offset:8720
	v_pk_fma_f32 v[184:185], v[82:83], v[188:189], v[168:169] op_sel:[1,1,0] op_sel_hi:[1,0,1] neg_lo:[1,0,0]
	v_pk_fma_f32 v[186:187], v[82:83], v[188:189], v[184:185] op_sel_hi:[0,1,1]
	v_mov_b32_e32 v103, v186
	v_mov_b32_e32 v112, v187
	v_cvt_pk_bf16_f32 v190, v186, v187
	ds_write_b32 v191, v190 offset:8448
	s_waitcnt vmcnt(0) lgkmcnt(0)
	ds_read_b128 v[72:75], v81 offset:8448
	ds_read_b128 v[104:107], v81 offset:8512
	s_waitcnt lgkmcnt(1)
	v_mfma_f32_16x16x32_bf16 v[72:75], v[72:75], v[32:35], 0
	s_waitcnt lgkmcnt(0)
	v_mfma_f32_16x16x32_bf16 v[72:75], v[104:107], v[28:31], v[72:75]
	ds_read_b128 v[104:107], v81 offset:8576
	s_waitcnt lgkmcnt(0)
	v_mfma_f32_16x16x32_bf16 v[72:75], v[104:107], v[24:27], v[72:75]
	ds_read_b128 v[104:107], v81 offset:8640
	s_waitcnt lgkmcnt(0)
	v_mfma_f32_16x16x32_bf16 v[72:75], v[104:107], v[20:23], v[72:75]
	v_mfma_f32_16x16x32_bf16 v[104:107], v[76:79], v[40:43], 0
	s_nop 7
	ds_write2_b32 v88, v104, v108 offset1:16
	ds_write2_b32 v88, v105, v109 offset0:132 offset1:148
	ds_write2_b32 v89, v106, v110 offset0:8 offset1:24
	ds_write2_b32 v89, v107, v111 offset0:140 offset1:156
	v_mfma_f32_16x16x32_bf16 v[104:107], v[76:79], v[48:51], 0
	v_mfma_f32_16x16x32_bf16 v[108:111], v[76:79], v[44:47], 0
	s_nop 7
	ds_write2_b32 v88, v104, v108 offset0:32 offset1:48
	ds_write2_b32 v88, v105, v109 offset0:164 offset1:180
	ds_write2_b32 v89, v106, v110 offset0:40 offset1:56
	ds_write2_b32 v89, v107, v111 offset0:172 offset1:188
	v_mfma_f32_16x16x32_bf16 v[104:107], v[76:79], v[56:59], 0
	v_mfma_f32_16x16x32_bf16 v[108:111], v[76:79], v[52:55], 0
	s_nop 7
	ds_write2_b32 v88, v104, v108 offset0:64 offset1:80
	ds_write2_b32 v88, v105, v109 offset0:196 offset1:212
	ds_write2_b32 v89, v106, v110 offset0:72 offset1:88
	ds_write2_b32 v89, v107, v111 offset0:204 offset1:220
	v_mfma_f32_16x16x32_bf16 v[104:107], v[76:79], v[64:67], 0
	v_mfma_f32_16x16x32_bf16 v[76:79], v[76:79], v[60:63], 0
	s_nop 7
	ds_write2_b32 v88, v104, v76 offset0:96 offset1:112
	ds_write2_b32 v88, v105, v77 offset0:228 offset1:244
	ds_write2_b32 v89, v106, v78 offset0:104 offset1:120
	ds_write2_b32 v89, v107, v79 offset0:236 offset1:252
	s_waitcnt vmcnt(0) lgkmcnt(0)
	ds_read2st64_b32 v[76:77], v91 offset0:30 offset1:31
	ds_read2st64_b32 v[140:141], v84 offset0:28 offset1:29
	ds_read2st64_b32 v[142:143], v85 offset0:26 offset1:27
	ds_read2st64_b32 v[144:145], v92 offset0:24 offset1:25
	ds_read2st64_b32 v[146:147], v93 offset0:22 offset1:23
	ds_read2st64_b32 v[148:149], v94 offset0:20 offset1:21
	ds_read2st64_b32 v[150:151], v95 offset0:18 offset1:19
	ds_read2st64_b32 v[152:153], v96 offset0:16 offset1:17
	ds_read2st64_b32 v[154:155], v97 offset0:14 offset1:15
	ds_read2st64_b32 v[156:157], v98 offset0:12 offset1:13
	ds_read2st64_b32 v[158:159], v99 offset0:10 offset1:11
	ds_read2st64_b32 v[160:161], v100 offset0:8 offset1:9
	ds_read2st64_b32 v[162:163], v101 offset0:6 offset1:7
	ds_read2st64_b32 v[164:165], v102 offset0:4 offset1:5
	ds_read2_b32 v[166:167], v87 offset0:132 offset1:196
	ds_read2st64_b32 v[168:169], v87 offset1:1
	v_mov_b32_e32 v186, v103
	v_mov_b32_e32 v187, v112
	v_mfma_f32_16x16x32_bf16 v[40:43], v[68:71], v[40:43], 0
	s_waitcnt lgkmcnt(0)
	v_pk_fma_f32 v[184:185], v[82:83], v[186:187], v[76:77] op_sel:[1,1,0] op_sel_hi:[1,0,1] neg_lo:[1,0,0]
	v_pk_fma_f32 v[188:189], v[82:83], v[186:187], v[184:185] op_sel_hi:[0,1,1]
	v_cvt_pk_bf16_f32 v190, v188, v189
	v_and_b32_e32 v191, 63, v207
	v_lshl_add_u32 v191, v191, 1, v86
	ds_write_b32 v191, v190 offset:12528
	v_pk_fma_f32 v[184:185], v[82:83], v[188:189], v[140:141] op_sel:[1,1,0] op_sel_hi:[1,0,1] neg_lo:[1,0,0]
	v_pk_fma_f32 v[186:187], v[82:83], v[188:189], v[184:185] op_sel_hi:[0,1,1]
	v_cvt_pk_bf16_f32 v190, v186, v187
	ds_write_b32 v191, v190 offset:12256
	v_pk_fma_f32 v[184:185], v[82:83], v[186:187], v[142:143] op_sel:[1,1,0] op_sel_hi:[1,0,1] neg_lo:[1,0,0]
	v_pk_fma_f32 v[188:189], v[82:83], v[186:187], v[184:185] op_sel_hi:[0,1,1]
	v_cvt_pk_bf16_f32 v190, v188, v189
	ds_write_b32 v191, v190 offset:11984
	v_pk_fma_f32 v[184:185], v[82:83], v[188:189], v[144:145] op_sel:[1,1,0] op_sel_hi:[1,0,1] neg_lo:[1,0,0]
	v_pk_fma_f32 v[186:187], v[82:83], v[188:189], v[184:185] op_sel_hi:[0,1,1]
	v_cvt_pk_bf16_f32 v190, v186, v187
	ds_write_b32 v191, v190 offset:11712
	v_pk_fma_f32 v[184:185], v[82:83], v[186:187], v[146:147] op_sel:[1,1,0] op_sel_hi:[1,0,1] neg_lo:[1,0,0]
	v_pk_fma_f32 v[188:189], v[82:83], v[186:187], v[184:185] op_sel_hi:[0,1,1]
	v_cvt_pk_bf16_f32 v190, v188, v189
	ds_write_b32 v191, v190 offset:11440
	v_pk_fma_f32 v[184:185], v[82:83], v[188:189], v[148:149] op_sel:[1,1,0] op_sel_hi:[1,0,1] neg_lo:[1,0,0]
	v_pk_fma_f32 v[186:187], v[82:83], v[188:189], v[184:185] op_sel_hi:[0,1,1]
	v_cvt_pk_bf16_f32 v190, v186, v187
	ds_write_b32 v191, v190 offset:11168
	v_pk_fma_f32 v[184:185], v[82:83], v[186:187], v[150:151] op_sel:[1,1,0] op_sel_hi:[1,0,1] neg_lo:[1,0,0]
	v_pk_fma_f32 v[188:189], v[82:83], v[186:187], v[184:185] op_sel_hi:[0,1,1]
	v_cvt_pk_bf16_f32 v190, v188, v189
	ds_write_b32 v191, v190 offset:10896
	v_pk_fma_f32 v[184:185], v[82:83], v[188:189], v[152:153] op_sel:[1,1,0] op_sel_hi:[1,0,1] neg_lo:[1,0,0]
	v_pk_fma_f32 v[186:187], v[82:83], v[188:189], v[184:185] op_sel_hi:[0,1,1]
	v_cvt_pk_bf16_f32 v190, v186, v187
	ds_write_b32 v191, v190 offset:10624
	v_pk_fma_f32 v[184:185], v[82:83], v[186:187], v[154:155] op_sel:[1,1,0] op_sel_hi:[1,0,1] neg_lo:[1,0,0]
	v_pk_fma_f32 v[188:189], v[82:83], v[186:187], v[184:185] op_sel_hi:[0,1,1]
	v_cvt_pk_bf16_f32 v190, v188, v189
	ds_write_b32 v191, v190 offset:10352
	v_pk_fma_f32 v[184:185], v[82:83], v[188:189], v[156:157] op_sel:[1,1,0] op_sel_hi:[1,0,1] neg_lo:[1,0,0]
	v_pk_fma_f32 v[186:187], v[82:83], v[188:189], v[184:185] op_sel_hi:[0,1,1]
	v_cvt_pk_bf16_f32 v190, v186, v187
	ds_write_b32 v191, v190 offset:10080
	v_pk_fma_f32 v[184:185], v[82:83], v[186:187], v[158:159] op_sel:[1,1,0] op_sel_hi:[1,0,1] neg_lo:[1,0,0]
	v_pk_fma_f32 v[188:189], v[82:83], v[186:187], v[184:185] op_sel_hi:[0,1,1]
	v_cvt_pk_bf16_f32 v190, v188, v189
	ds_write_b32 v191, v190 offset:9808
	v_pk_fma_f32 v[184:185], v[82:83], v[188:189], v[160:161] op_sel:[1,1,0] op_sel_hi:[1,0,1] neg_lo:[1,0,0]
	v_pk_fma_f32 v[186:187], v[82:83], v[188:189], v[184:185] op_sel_hi:[0,1,1]
	v_cvt_pk_bf16_f32 v190, v186, v187
	ds_write_b32 v191, v190 offset:9536
	v_pk_fma_f32 v[184:185], v[82:83], v[186:187], v[162:163] op_sel:[1,1,0] op_sel_hi:[1,0,1] neg_lo:[1,0,0]
	v_pk_fma_f32 v[188:189], v[82:83], v[186:187], v[184:185] op_sel_hi:[0,1,1]
	v_cvt_pk_bf16_f32 v190, v188, v189
	ds_write_b32 v191, v190 offset:9264
	v_pk_fma_f32 v[184:185], v[82:83], v[188:189], v[164:165] op_sel:[1,1,0] op_sel_hi:[1,0,1] neg_lo:[1,0,0]
	v_pk_fma_f32 v[186:187], v[82:83], v[188:189], v[184:185] op_sel_hi:[0,1,1]
	v_cvt_pk_bf16_f32 v190, v186, v187
	ds_write_b32 v191, v190 offset:8992
	v_pk_fma_f32 v[184:185], v[82:83], v[186:187], v[166:167] op_sel:[1,1,0] op_sel_hi:[1,0,1] neg_lo:[1,0,0]
	v_pk_fma_f32 v[188:189], v[82:83], v[186:187], v[184:185] op_sel_hi:[0,1,1]
	v_cvt_pk_bf16_f32 v190, v188, v189
	ds_write_b32 v191, v190 offset:8720
	v_pk_fma_f32 v[184:185], v[82:83], v[188:189], v[168:169] op_sel:[1,1,0] op_sel_hi:[1,0,1] neg_lo:[1,0,0]
	v_pk_fma_f32 v[186:187], v[82:83], v[188:189], v[184:185] op_sel_hi:[0,1,1]
	v_mov_b32_e32 v103, v186
	v_mov_b32_e32 v108, v187
	v_cvt_pk_bf16_f32 v190, v186, v187
	ds_write_b32 v191, v190 offset:8448
	s_waitcnt vmcnt(0) lgkmcnt(0)
	ds_read_b128 v[76:79], v81 offset:8448
	ds_read_b128 v[104:107], v81 offset:8512
	s_waitcnt lgkmcnt(1)
	v_mfma_f32_16x16x32_bf16 v[76:79], v[76:79], v[32:35], 0
	s_waitcnt lgkmcnt(0)
	v_mfma_f32_16x16x32_bf16 v[76:79], v[104:107], v[28:31], v[76:79]
	ds_read_b128 v[104:107], v81 offset:8576
	s_waitcnt lgkmcnt(0)
	v_mfma_f32_16x16x32_bf16 v[76:79], v[104:107], v[24:27], v[76:79]
	ds_read_b128 v[104:107], v81 offset:8640
	ds_write2_b32 v88, v40, v36 offset1:16
	ds_write2_b32 v88, v41, v37 offset0:132 offset1:148
	ds_write2_b32 v89, v42, v38 offset0:8 offset1:24
	ds_write2_b32 v89, v43, v39 offset0:140 offset1:156
	v_mfma_f32_16x16x32_bf16 v[36:39], v[68:71], v[48:51], 0
	v_mfma_f32_16x16x32_bf16 v[40:43], v[68:71], v[44:47], 0
	s_nop 7
	ds_write2_b32 v88, v36, v40 offset0:32 offset1:48
	ds_write2_b32 v88, v37, v41 offset0:164 offset1:180
	ds_write2_b32 v89, v38, v42 offset0:40 offset1:56
	ds_write2_b32 v89, v39, v43 offset0:172 offset1:188
	v_mfma_f32_16x16x32_bf16 v[36:39], v[68:71], v[56:59], 0
	v_mfma_f32_16x16x32_bf16 v[40:43], v[68:71], v[52:55], 0
	s_nop 7
	ds_write2_b32 v88, v36, v40 offset0:64 offset1:80
	ds_write2_b32 v88, v37, v41 offset0:196 offset1:212
	ds_write2_b32 v89, v38, v42 offset0:72 offset1:88
	ds_write2_b32 v89, v39, v43 offset0:204 offset1:220
	v_mfma_f32_16x16x32_bf16 v[36:39], v[68:71], v[64:67], 0
	v_mfma_f32_16x16x32_bf16 v[40:43], v[68:71], v[60:63], 0
	s_nop 7
	ds_write2_b32 v88, v36, v40 offset0:96 offset1:112
	ds_write2_b32 v88, v37, v41 offset0:228 offset1:244
	ds_write2_b32 v89, v38, v42 offset0:104 offset1:120
	ds_write2_b32 v89, v39, v43 offset0:236 offset1:252
	s_waitcnt vmcnt(0) lgkmcnt(0)
	ds_read2st64_b32 v[36:37], v91 offset0:30 offset1:31
	ds_read2st64_b32 v[140:141], v84 offset0:28 offset1:29
	ds_read2st64_b32 v[142:143], v85 offset0:26 offset1:27
	ds_read2st64_b32 v[144:145], v92 offset0:24 offset1:25
	ds_read2st64_b32 v[146:147], v93 offset0:22 offset1:23
	ds_read2st64_b32 v[148:149], v94 offset0:20 offset1:21
	ds_read2st64_b32 v[150:151], v95 offset0:18 offset1:19
	ds_read2st64_b32 v[152:153], v96 offset0:16 offset1:17
	ds_read2st64_b32 v[154:155], v97 offset0:14 offset1:15
	ds_read2st64_b32 v[156:157], v98 offset0:12 offset1:13
	ds_read2st64_b32 v[158:159], v99 offset0:10 offset1:11
	ds_read2st64_b32 v[160:161], v100 offset0:8 offset1:9
	ds_read2st64_b32 v[162:163], v101 offset0:6 offset1:7
	ds_read2st64_b32 v[164:165], v102 offset0:4 offset1:5
	ds_read2_b32 v[166:167], v87 offset0:132 offset1:196
	ds_read2st64_b32 v[168:169], v87 offset1:1
	v_mov_b32_e32 v186, v103
	v_mov_b32_e32 v187, v108
	s_waitcnt lgkmcnt(0)
	v_mfma_f32_16x16x32_bf16 v[76:79], v[104:107], v[20:23], v[76:79]
	v_pk_fma_f32 v[184:185], v[82:83], v[186:187], v[36:37] op_sel:[1,1,0] op_sel_hi:[1,0,1] neg_lo:[1,0,0]
	v_pk_fma_f32 v[188:189], v[82:83], v[186:187], v[184:185] op_sel_hi:[0,1,1]
	v_cvt_pk_bf16_f32 v190, v188, v189
	v_and_b32_e32 v191, 63, v207
	v_lshl_add_u32 v191, v191, 1, v86
	ds_write_b32 v191, v190 offset:12528
	v_pk_fma_f32 v[184:185], v[82:83], v[188:189], v[140:141] op_sel:[1,1,0] op_sel_hi:[1,0,1] neg_lo:[1,0,0]
	v_pk_fma_f32 v[186:187], v[82:83], v[188:189], v[184:185] op_sel_hi:[0,1,1]
	v_cvt_pk_bf16_f32 v190, v186, v187
	ds_write_b32 v191, v190 offset:12256
	v_pk_fma_f32 v[184:185], v[82:83], v[186:187], v[142:143] op_sel:[1,1,0] op_sel_hi:[1,0,1] neg_lo:[1,0,0]
	v_pk_fma_f32 v[188:189], v[82:83], v[186:187], v[184:185] op_sel_hi:[0,1,1]
	v_cvt_pk_bf16_f32 v190, v188, v189
	ds_write_b32 v191, v190 offset:11984
	v_pk_fma_f32 v[184:185], v[82:83], v[188:189], v[144:145] op_sel:[1,1,0] op_sel_hi:[1,0,1] neg_lo:[1,0,0]
	v_pk_fma_f32 v[186:187], v[82:83], v[188:189], v[184:185] op_sel_hi:[0,1,1]
	v_cvt_pk_bf16_f32 v190, v186, v187
	ds_write_b32 v191, v190 offset:11712
	v_pk_fma_f32 v[184:185], v[82:83], v[186:187], v[146:147] op_sel:[1,1,0] op_sel_hi:[1,0,1] neg_lo:[1,0,0]
	v_pk_fma_f32 v[188:189], v[82:83], v[186:187], v[184:185] op_sel_hi:[0,1,1]
	v_cvt_pk_bf16_f32 v190, v188, v189
	ds_write_b32 v191, v190 offset:11440
	v_pk_fma_f32 v[184:185], v[82:83], v[188:189], v[148:149] op_sel:[1,1,0] op_sel_hi:[1,0,1] neg_lo:[1,0,0]
	v_pk_fma_f32 v[186:187], v[82:83], v[188:189], v[184:185] op_sel_hi:[0,1,1]
	v_cvt_pk_bf16_f32 v190, v186, v187
	ds_write_b32 v191, v190 offset:11168
	v_pk_fma_f32 v[184:185], v[82:83], v[186:187], v[150:151] op_sel:[1,1,0] op_sel_hi:[1,0,1] neg_lo:[1,0,0]
	v_pk_fma_f32 v[188:189], v[82:83], v[186:187], v[184:185] op_sel_hi:[0,1,1]
	v_cvt_pk_bf16_f32 v190, v188, v189
	ds_write_b32 v191, v190 offset:10896
	v_pk_fma_f32 v[184:185], v[82:83], v[188:189], v[152:153] op_sel:[1,1,0] op_sel_hi:[1,0,1] neg_lo:[1,0,0]
	v_pk_fma_f32 v[186:187], v[82:83], v[188:189], v[184:185] op_sel_hi:[0,1,1]
	v_cvt_pk_bf16_f32 v190, v186, v187
	ds_write_b32 v191, v190 offset:10624
	v_pk_fma_f32 v[184:185], v[82:83], v[186:187], v[154:155] op_sel:[1,1,0] op_sel_hi:[1,0,1] neg_lo:[1,0,0]
	v_pk_fma_f32 v[188:189], v[82:83], v[186:187], v[184:185] op_sel_hi:[0,1,1]
	v_cvt_pk_bf16_f32 v190, v188, v189
	ds_write_b32 v191, v190 offset:10352
	v_pk_fma_f32 v[184:185], v[82:83], v[188:189], v[156:157] op_sel:[1,1,0] op_sel_hi:[1,0,1] neg_lo:[1,0,0]
	v_pk_fma_f32 v[186:187], v[82:83], v[188:189], v[184:185] op_sel_hi:[0,1,1]
	v_cvt_pk_bf16_f32 v190, v186, v187
	ds_write_b32 v191, v190 offset:10080
	v_pk_fma_f32 v[184:185], v[82:83], v[186:187], v[158:159] op_sel:[1,1,0] op_sel_hi:[1,0,1] neg_lo:[1,0,0]
	v_pk_fma_f32 v[188:189], v[82:83], v[186:187], v[184:185] op_sel_hi:[0,1,1]
	v_cvt_pk_bf16_f32 v190, v188, v189
	ds_write_b32 v191, v190 offset:9808
	v_pk_fma_f32 v[184:185], v[82:83], v[188:189], v[160:161] op_sel:[1,1,0] op_sel_hi:[1,0,1] neg_lo:[1,0,0]
	v_pk_fma_f32 v[186:187], v[82:83], v[188:189], v[184:185] op_sel_hi:[0,1,1]
	v_cvt_pk_bf16_f32 v190, v186, v187
	ds_write_b32 v191, v190 offset:9536
	v_pk_fma_f32 v[184:185], v[82:83], v[186:187], v[162:163] op_sel:[1,1,0] op_sel_hi:[1,0,1] neg_lo:[1,0,0]
	v_pk_fma_f32 v[188:189], v[82:83], v[186:187], v[184:185] op_sel_hi:[0,1,1]
	v_cvt_pk_bf16_f32 v190, v188, v189
	ds_write_b32 v191, v190 offset:9264
	v_pk_fma_f32 v[184:185], v[82:83], v[188:189], v[164:165] op_sel:[1,1,0] op_sel_hi:[1,0,1] neg_lo:[1,0,0]
	v_pk_fma_f32 v[186:187], v[82:83], v[188:189], v[184:185] op_sel_hi:[0,1,1]
	v_cvt_pk_bf16_f32 v190, v186, v187
	ds_write_b32 v191, v190 offset:8992
	v_pk_fma_f32 v[184:185], v[82:83], v[186:187], v[166:167] op_sel:[1,1,0] op_sel_hi:[1,0,1] neg_lo:[1,0,0]
	v_pk_fma_f32 v[188:189], v[82:83], v[186:187], v[184:185] op_sel_hi:[0,1,1]
	v_cvt_pk_bf16_f32 v190, v188, v189
	ds_write_b32 v191, v190 offset:8720
	v_pk_fma_f32 v[184:185], v[82:83], v[188:189], v[168:169] op_sel:[1,1,0] op_sel_hi:[1,0,1] neg_lo:[1,0,0]
	v_pk_fma_f32 v[186:187], v[82:83], v[188:189], v[184:185] op_sel_hi:[0,1,1]
	v_mov_b32_e32 v36, v186
	v_mov_b32_e32 v37, v187
	v_cvt_pk_bf16_f32 v190, v186, v187
	ds_write_b32 v191, v190 offset:8448
	s_waitcnt vmcnt(0) lgkmcnt(0)
	ds_read_b128 v[36:39], v81 offset:8448
	s_waitcnt lgkmcnt(0)
	v_mfma_f32_16x16x32_bf16 v[32:35], v[36:39], v[32:35], 0
	ds_read_b128 v[36:39], v81 offset:8512
	s_waitcnt lgkmcnt(0)
	v_mfma_f32_16x16x32_bf16 v[28:31], v[36:39], v[28:31], v[32:35]
	s_nop 4
	ds_read_b128 v[32:35], v81 offset:8576
	s_waitcnt lgkmcnt(0)
	v_mfma_f32_16x16x32_bf16 v[24:27], v[32:35], v[24:27], v[28:31]
	s_nop 2
	ds_read_b128 v[28:31], v81 offset:8640
	s_waitcnt lgkmcnt(0)
	v_mfma_f32_16x16x32_bf16 v[20:23], v[28:31], v[20:23], v[24:27]
	s_nop 7
	v_pk_add_f32 v[24:25], v[0:1], v[20:21]
	v_and_or_b32 v0, v90, 15, v80
	v_add_u32_e32 v20, s6, v0
	v_ashrrev_i32_e32 v21, 31, v20
	v_lshrrev_b32_e32 v1, 2, v90
	v_lshl_add_u64 v[20:21], v[20:21], 2, s[76:77]
	v_and_b32_e32 v1, 12, v1
	global_load_dword v28, v[20:21], off
	v_add_u32_e32 v20, s8, v1
	v_ashrrev_i32_e32 v21, 31, v20
	v_ashrrev_i32_e32 v1, 31, v0
	v_lshlrev_b64 v[26:27], 9, v[20:21]
	v_lshl_add_u64 v[26:27], v[26:27], 0, v[0:1]
	v_lshl_add_u64 v[30:31], v[26:27], 1, s[36:37]
	global_load_ushort v29, v[30:31], off
	global_load_ushort v141, v[30:31], off offset:1024
	global_load_ushort v142, v[30:31], off offset:2048
	global_load_ushort v143, v[30:31], off offset:3072
	s_mov_b64 s[0:1], 0x4000
	v_lshl_add_u64 v[156:157], v[30:31], 0, s[0:1]
	global_load_ushort v144, v[156:157], off
	global_load_ushort v145, v[156:157], off offset:1024
	global_load_ushort v146, v[156:157], off offset:2048
	global_load_ushort v147, v[156:157], off offset:3072
	s_mov_b64 s[0:1], 0x8000
	v_lshl_add_u64 v[158:159], v[30:31], 0, s[0:1]
	global_load_ushort v148, v[158:159], off
	global_load_ushort v149, v[158:159], off offset:1024
	global_load_ushort v150, v[158:159], off offset:2048
	global_load_ushort v151, v[158:159], off offset:3072
	s_mov_b64 s[0:1], 0xc000
	v_lshl_add_u64 v[160:161], v[30:31], 0, s[0:1]
	global_load_ushort v152, v[160:161], off
	global_load_ushort v153, v[160:161], off offset:1024
	global_load_ushort v154, v[160:161], off offset:2048
	global_load_ushort v155, v[160:161], off offset:3072
	s_waitcnt vmcnt(0) lgkmcnt(0)
	v_lshlrev_b32_e32 v29, 16, v29
	v_fma_f32 v24, v28, v29, v24
	v_mul_f32_e32 v29, 0x3d372713, v24
	v_mul_f32_e32 v29, v24, v29
	v_fma_f32 v29, v24, v29, v24
	v_mul_f32_e32 v29, 0x3f4c422a, v29
	v_cmp_nlt_f32_e64 s[0:1], |v29|, s10
	s_and_saveexec_b64 s[2:3], s[0:1]
	s_xor_b64 s[0:1], exec, s[2:3]
	s_cbranch_execz .LBB0_1813
	v_add_f32_e64 v30, |v29|, |v29|
	v_mul_f32_e32 v31, 0x3fb8aa3b, v30
	v_rndne_f32_e32 v32, v31
	s_mov_b32 s2, 0x3fb8aa3b
	v_sub_f32_e32 v33, v31, v32
	v_fma_f32 v31, v30, s2, -v31
	v_fmac_f32_e32 v31, 0x32a5705f, v30
	v_add_f32_e32 v31, v33, v31
	v_cvt_i32_f32_e32 v32, v32
	v_exp_f32_e32 v31, v31
	s_mov_b32 s2, 0xc2ce8ed0
	v_cmp_ngt_f32_e32 vcc, s2, v30
	s_mov_b32 s2, 0x42b17218
	v_ldexp_f32 v31, v31, v32
	v_cndmask_b32_e32 v31, 0, v31, vcc
	v_cmp_nlt_f32_e32 vcc, s2, v30
	s_nop 1
	v_cndmask_b32_e32 v30, v235, v31, vcc
	v_add_f32_e32 v30, 1.0, v30
	v_rcp_f32_e32 v30, v30
	s_nop 0
	v_fma_f32 v30, v30, -2.0, 1.0
